# SwiGLU epilogue ACT stores: default cache policy instead of nt
# baseline (speedup 1.0000x reference)
; __device__ __forceinline__ unsigned cvt_pk_bf16(float lo, float hi) { unsigned r; asm("v_cvt_pk_bf16_f32 %0, %1, %2" : "=v"(r) : "v"(lo), "v"(hi)); return r; }
;     __device__ __forceinline__ void operator()(const Acc& acc, const Unit& u, int wr, int wc, int fr, int fq) const {
;         const int row0 = u.pm * 256 + wr * 64 + fr, h0 = u.pn * 128 + wc * 32 + 8 * fq;
; #pragma unroll
;         for (int ai = 0; ai < 2; ++ai)
; #pragma unroll
;             for (int m = 0; m < 4; ++m) { bf16_t* rp = ACT + (size_t)(row0 + ai * 128 + m * 16) * FF + h0; float v[8];
; #pragma unroll
;                 for (int n = 0; n < 2; ++n) { const f32x4 a = acc[ai][0][m][n], b = acc[ai][1][m][n];
;                     const f32x4 t = a * (-LOG2E); f32x4 e; e.x = __builtin_amdgcn_exp2f(t.x); e.y = __builtin_amdgcn_exp2f(t.y); e.z = __builtin_amdgcn_exp2f(t.z); e.w = __builtin_amdgcn_exp2f(t.w);
;                     const f32x4 d = e + 1.0f; f32x4 r; r.x = __builtin_amdgcn_rcpf(d.x); r.y = __builtin_amdgcn_rcpf(d.y); r.z = __builtin_amdgcn_rcpf(d.z); r.w = __builtin_amdgcn_rcpf(d.w);
;                     const f32x4 o = (a * b) * r; v[4 * n + 0] = o.x; v[4 * n + 1] = o.y; v[4 * n + 2] = o.z; v[4 * n + 3] = o.w; }
;                 u32x4 w; w.x = cvt_pk_bf16(v[0], v[1]); w.y = cvt_pk_bf16(v[2], v[3]); w.z = cvt_pk_bf16(v[4], v[5]); w.w = cvt_pk_bf16(v[6], v[7]); __builtin_nontemporal_store(w, (u32x4*)rp); }
.LBB0_259:
	v_pk_mul_f32 v[152:153], v[126:127], s[10:11] op_sel_hi:[1,0]
	v_pk_mul_f32 v[122:123], v[126:127], v[122:123]
	v_pk_mul_f32 v[126:127], v[116:117], s[10:11] op_sel_hi:[1,0]
	v_pk_mul_f32 v[154:155], v[124:125], s[10:11] op_sel_hi:[1,0]
	v_pk_mul_f32 v[120:121], v[124:125], v[120:121]
	v_pk_mul_f32 v[124:125], v[118:119], s[10:11] op_sel_hi:[1,0]
	v_exp_f32_e32 v126, v126
	v_exp_f32_e32 v127, v127
	v_exp_f32_e32 v154, v154
	v_exp_f32_e32 v152, v152
	v_exp_f32_e32 v153, v153
	v_exp_f32_e32 v155, v155
	v_exp_f32_e32 v124, v124
	v_exp_f32_e32 v125, v125
	v_pk_add_f32 v[126:127], v[126:127], 1.0 op_sel_hi:[1,0]
	v_pk_add_f32 v[152:153], v[152:153], 1.0 op_sel_hi:[1,0]
	v_pk_add_f32 v[154:155], v[154:155], 1.0 op_sel_hi:[1,0]
	v_pk_add_f32 v[124:125], v[124:125], 1.0 op_sel_hi:[1,0]
	v_rcp_f32_e32 v126, v126
	v_rcp_f32_e32 v127, v127
	v_rcp_f32_e32 v154, v154
	v_rcp_f32_e32 v155, v155
	v_rcp_f32_e32 v152, v152
	v_rcp_f32_e32 v153, v153
	v_rcp_f32_e32 v124, v124
	v_rcp_f32_e32 v125, v125
	v_lshl_or_b32 v150, s57, 7, v144
	v_lshl_add_u32 v148, s42, 8, v142
	v_ashrrev_i32_e32 v151, 31, v150
	v_mov_b64_e32 v[140:141], s[14:15]
	v_pk_mul_f32 v[112:113], v[116:117], v[112:113]
	v_mad_i64_i32 v[156:157], s[44:45], v148, s56, v[140:141]
	v_pk_mul_f32 v[114:115], v[118:119], v[114:115]
	v_pk_mul_f32 v[116:117], v[126:127], v[112:113]
	v_lshlrev_b64 v[112:113], 1, v[150:151]
	v_pk_mul_f32 v[122:123], v[152:153], v[122:123]
	v_pk_mul_f32 v[120:121], v[154:155], v[120:121]
	v_pk_mul_f32 v[118:119], v[124:125], v[114:115]
	v_lshl_add_u64 v[124:125], v[156:157], 0, v[112:113]
	v_cvt_pk_bf16_f32 v114, v120, v121
	v_cvt_pk_bf16_f32 v115, v122, v123
	v_cvt_pk_bf16_f32 v116, v116, v117
	v_cvt_pk_bf16_f32 v117, v118, v119
	global_store_dwordx4 v[124:125], v[114:117], off
	v_pk_mul_f32 v[106:107], v[110:111], v[106:107]
	v_pk_mul_f32 v[104:105], v[108:109], v[104:105]
	v_pk_mul_f32 v[114:115], v[110:111], s[10:11] op_sel_hi:[1,0]
	v_pk_mul_f32 v[116:117], v[108:109], s[10:11] op_sel_hi:[1,0]
	v_pk_mul_f32 v[108:109], v[102:103], s[10:11] op_sel_hi:[1,0]
	v_pk_mul_f32 v[110:111], v[100:101], s[10:11] op_sel_hi:[1,0]
	v_exp_f32_e32 v108, v108
	v_exp_f32_e32 v110, v110
	v_exp_f32_e32 v109, v109
	v_exp_f32_e32 v111, v111
	v_exp_f32_e32 v116, v116
	v_exp_f32_e32 v114, v114
	v_exp_f32_e32 v115, v115
	v_exp_f32_e32 v117, v117
	v_pk_add_f32 v[108:109], v[108:109], 1.0 op_sel_hi:[1,0]
	v_pk_add_f32 v[110:111], v[110:111], 1.0 op_sel_hi:[1,0]
	v_pk_add_f32 v[114:115], v[114:115], 1.0 op_sel_hi:[1,0]
	v_pk_add_f32 v[116:117], v[116:117], 1.0 op_sel_hi:[1,0]
	v_rcp_f32_e32 v110, v110
	v_rcp_f32_e32 v108, v108
	v_rcp_f32_e32 v109, v109
	v_rcp_f32_e32 v111, v111
	v_rcp_f32_e32 v116, v116
	v_rcp_f32_e32 v117, v117
	v_rcp_f32_e32 v114, v114
	v_rcp_f32_e32 v115, v115
	v_or_b32_e32 v118, 16, v148
	v_pk_mul_f32 v[98:99], v[102:103], v[98:99]
	v_pk_mul_f32 v[96:97], v[100:101], v[96:97]
	v_mad_i64_i32 v[118:119], s[44:45], v118, s56, v[140:141]
	v_pk_mul_f32 v[100:101], v[108:109], v[98:99]
	v_pk_mul_f32 v[98:99], v[110:111], v[96:97]
	v_pk_mul_f32 v[106:107], v[114:115], v[106:107]
	v_pk_mul_f32 v[104:105], v[116:117], v[104:105]
	v_lshl_add_u64 v[102:103], v[118:119], 0, v[112:113]
	v_cvt_pk_bf16_f32 v96, v104, v105
	v_cvt_pk_bf16_f32 v97, v106, v107
	v_cvt_pk_bf16_f32 v98, v98, v99
	v_cvt_pk_bf16_f32 v99, v100, v101
	global_store_dwordx4 v[102:103], v[96:99], off
	v_pk_mul_f32 v[90:91], v[94:95], v[90:91]
	v_pk_mul_f32 v[88:89], v[92:93], v[88:89]
	v_pk_mul_f32 v[96:97], v[94:95], s[10:11] op_sel_hi:[1,0]
	v_pk_mul_f32 v[98:99], v[92:93], s[10:11] op_sel_hi:[1,0]
	v_pk_mul_f32 v[92:93], v[86:87], s[10:11] op_sel_hi:[1,0]
	v_pk_mul_f32 v[94:95], v[84:85], s[10:11] op_sel_hi:[1,0]
	v_exp_f32_e32 v92, v92
	v_exp_f32_e32 v94, v94
	v_exp_f32_e32 v93, v93
	v_exp_f32_e32 v95, v95
	v_exp_f32_e32 v98, v98
	v_exp_f32_e32 v96, v96
	v_exp_f32_e32 v97, v97
	v_exp_f32_e32 v99, v99
	v_pk_add_f32 v[92:93], v[92:93], 1.0 op_sel_hi:[1,0]
	v_pk_add_f32 v[94:95], v[94:95], 1.0 op_sel_hi:[1,0]
	v_pk_add_f32 v[96:97], v[96:97], 1.0 op_sel_hi:[1,0]
	v_pk_add_f32 v[98:99], v[98:99], 1.0 op_sel_hi:[1,0]
	v_rcp_f32_e32 v94, v94
	v_rcp_f32_e32 v92, v92
	v_rcp_f32_e32 v93, v93
	v_rcp_f32_e32 v95, v95
	v_rcp_f32_e32 v98, v98
	v_rcp_f32_e32 v99, v99
	v_rcp_f32_e32 v96, v96
	v_rcp_f32_e32 v97, v97
	v_or_b32_e32 v100, 32, v148
	v_pk_mul_f32 v[82:83], v[86:87], v[82:83]
	v_pk_mul_f32 v[80:81], v[84:85], v[80:81]
	v_mad_i64_i32 v[100:101], s[44:45], v100, s56, v[140:141]
	v_pk_mul_f32 v[84:85], v[92:93], v[82:83]
	v_pk_mul_f32 v[82:83], v[94:95], v[80:81]
	v_pk_mul_f32 v[90:91], v[96:97], v[90:91]
	v_pk_mul_f32 v[88:89], v[98:99], v[88:89]
	v_lshl_add_u64 v[86:87], v[100:101], 0, v[112:113]
	v_cvt_pk_bf16_f32 v80, v88, v89
	v_cvt_pk_bf16_f32 v81, v90, v91
	v_cvt_pk_bf16_f32 v82, v82, v83
	v_cvt_pk_bf16_f32 v83, v84, v85
	global_store_dwordx4 v[86:87], v[80:83], off
	v_pk_mul_f32 v[74:75], v[78:79], v[74:75]
	v_pk_mul_f32 v[72:73], v[76:77], v[72:73]
	v_pk_mul_f32 v[80:81], v[78:79], s[10:11] op_sel_hi:[1,0]
	v_pk_mul_f32 v[82:83], v[76:77], s[10:11] op_sel_hi:[1,0]
	v_pk_mul_f32 v[76:77], v[70:71], s[10:11] op_sel_hi:[1,0]
	v_pk_mul_f32 v[78:79], v[68:69], s[10:11] op_sel_hi:[1,0]
	v_exp_f32_e32 v76, v76
	v_exp_f32_e32 v78, v78
	v_exp_f32_e32 v77, v77
	v_exp_f32_e32 v79, v79
	v_exp_f32_e32 v82, v82
	v_exp_f32_e32 v80, v80
	v_exp_f32_e32 v81, v81
	v_exp_f32_e32 v83, v83
	v_pk_add_f32 v[76:77], v[76:77], 1.0 op_sel_hi:[1,0]
	v_pk_add_f32 v[78:79], v[78:79], 1.0 op_sel_hi:[1,0]
	v_pk_add_f32 v[80:81], v[80:81], 1.0 op_sel_hi:[1,0]
	v_pk_add_f32 v[82:83], v[82:83], 1.0 op_sel_hi:[1,0]
	v_rcp_f32_e32 v78, v78
; __device__ __forceinline__ unsigned cvt_pk_bf16(float lo, float hi) { unsigned r; asm("v_cvt_pk_bf16_f32 %0, %1, %2" : "=v"(r) : "v"(lo), "v"(hi)); return r; }
;     __device__ __forceinline__ void operator()(const Acc& acc, const Unit& u, int wr, int wc, int fr, int fq) const {
;         const int row0 = u.pm * 256 + wr * 64 + fr, h0 = u.pn * 128 + wc * 32 + 8 * fq;
; #pragma unroll
;         for (int ai = 0; ai < 2; ++ai)
; #pragma unroll
;             for (int m = 0; m < 4; ++m) { bf16_t* rp = ACT + (size_t)(row0 + ai * 128 + m * 16) * FF + h0; float v[8];
; #pragma unroll
;                 for (int n = 0; n < 2; ++n) { const f32x4 a = acc[ai][0][m][n], b = acc[ai][1][m][n];
;                     const f32x4 t = a * (-LOG2E); f32x4 e; e.x = __builtin_amdgcn_exp2f(t.x); e.y = __builtin_amdgcn_exp2f(t.y); e.z = __builtin_amdgcn_exp2f(t.z); e.w = __builtin_amdgcn_exp2f(t.w);
;                     const f32x4 d = e + 1.0f; f32x4 r; r.x = __builtin_amdgcn_rcpf(d.x); r.y = __builtin_amdgcn_rcpf(d.y); r.z = __builtin_amdgcn_rcpf(d.z); r.w = __builtin_amdgcn_rcpf(d.w);
;                     const f32x4 o = (a * b) * r; v[4 * n + 0] = o.x; v[4 * n + 1] = o.y; v[4 * n + 2] = o.z; v[4 * n + 3] = o.w; }
;                 u32x4 w; w.x = cvt_pk_bf16(v[0], v[1]); w.y = cvt_pk_bf16(v[2], v[3]); w.z = cvt_pk_bf16(v[4], v[5]); w.w = cvt_pk_bf16(v[6], v[7]); __builtin_nontemporal_store(w, (u32x4*)rp); }
	v_rcp_f32_e32 v76, v76
	v_rcp_f32_e32 v77, v77
	v_rcp_f32_e32 v79, v79
	v_rcp_f32_e32 v82, v82
	v_rcp_f32_e32 v83, v83
	v_rcp_f32_e32 v80, v80
	v_rcp_f32_e32 v81, v81
	v_or_b32_e32 v84, 48, v148
	v_pk_mul_f32 v[66:67], v[70:71], v[66:67]
	v_pk_mul_f32 v[64:65], v[68:69], v[64:65]
	v_mad_i64_i32 v[84:85], s[44:45], v84, s56, v[140:141]
	v_pk_mul_f32 v[68:69], v[76:77], v[66:67]
	v_pk_mul_f32 v[66:67], v[78:79], v[64:65]
	v_pk_mul_f32 v[74:75], v[80:81], v[74:75]
	v_pk_mul_f32 v[72:73], v[82:83], v[72:73]
	v_lshl_add_u64 v[70:71], v[84:85], 0, v[112:113]
	v_cvt_pk_bf16_f32 v64, v72, v73
	v_cvt_pk_bf16_f32 v65, v74, v75
	v_cvt_pk_bf16_f32 v66, v66, v67
	v_cvt_pk_bf16_f32 v67, v68, v69
	global_store_dwordx4 v[70:71], v[64:67], off
	v_pk_mul_f32 v[58:59], v[62:63], v[58:59]
	v_pk_mul_f32 v[56:57], v[60:61], v[56:57]
	v_pk_mul_f32 v[64:65], v[62:63], s[10:11] op_sel_hi:[1,0]
	v_pk_mul_f32 v[66:67], v[60:61], s[10:11] op_sel_hi:[1,0]
	v_pk_mul_f32 v[60:61], v[54:55], s[10:11] op_sel_hi:[1,0]
	v_pk_mul_f32 v[62:63], v[52:53], s[10:11] op_sel_hi:[1,0]
	v_exp_f32_e32 v60, v60
	v_exp_f32_e32 v62, v62
	v_exp_f32_e32 v61, v61
	v_exp_f32_e32 v63, v63
	v_exp_f32_e32 v66, v66
	v_exp_f32_e32 v64, v64
	v_exp_f32_e32 v65, v65
	v_exp_f32_e32 v67, v67
	v_pk_add_f32 v[60:61], v[60:61], 1.0 op_sel_hi:[1,0]
	v_pk_add_f32 v[62:63], v[62:63], 1.0 op_sel_hi:[1,0]
	v_pk_add_f32 v[64:65], v[64:65], 1.0 op_sel_hi:[1,0]
	v_pk_add_f32 v[66:67], v[66:67], 1.0 op_sel_hi:[1,0]
	v_rcp_f32_e32 v62, v62
	v_rcp_f32_e32 v60, v60
	v_rcp_f32_e32 v61, v61
	v_rcp_f32_e32 v63, v63
	v_rcp_f32_e32 v66, v66
	v_rcp_f32_e32 v67, v67
	v_rcp_f32_e32 v64, v64
	v_rcp_f32_e32 v65, v65
	v_add_u32_e32 v68, 0x80, v148
	v_pk_mul_f32 v[50:51], v[54:55], v[50:51]
	v_pk_mul_f32 v[48:49], v[52:53], v[48:49]
	v_mad_i64_i32 v[68:69], s[44:45], v68, s56, v[140:141]
	v_pk_mul_f32 v[52:53], v[60:61], v[50:51]
	v_pk_mul_f32 v[50:51], v[62:63], v[48:49]
	v_pk_mul_f32 v[58:59], v[64:65], v[58:59]
	v_pk_mul_f32 v[56:57], v[66:67], v[56:57]
	v_lshl_add_u64 v[54:55], v[68:69], 0, v[112:113]
	v_cvt_pk_bf16_f32 v48, v56, v57
	v_cvt_pk_bf16_f32 v49, v58, v59
	v_cvt_pk_bf16_f32 v50, v50, v51
	v_cvt_pk_bf16_f32 v51, v52, v53
	global_store_dwordx4 v[54:55], v[48:51], off
	v_pk_mul_f32 v[42:43], v[46:47], v[42:43]
	v_pk_mul_f32 v[40:41], v[44:45], v[40:41]
	v_pk_mul_f32 v[48:49], v[46:47], s[10:11] op_sel_hi:[1,0]
	v_pk_mul_f32 v[50:51], v[44:45], s[10:11] op_sel_hi:[1,0]
	v_pk_mul_f32 v[44:45], v[38:39], s[10:11] op_sel_hi:[1,0]
	v_pk_mul_f32 v[46:47], v[36:37], s[10:11] op_sel_hi:[1,0]
	v_exp_f32_e32 v44, v44
	v_exp_f32_e32 v46, v46
	v_exp_f32_e32 v45, v45
	v_exp_f32_e32 v47, v47
	v_exp_f32_e32 v50, v50
	v_exp_f32_e32 v48, v48
	v_exp_f32_e32 v49, v49
	v_exp_f32_e32 v51, v51
	v_pk_add_f32 v[44:45], v[44:45], 1.0 op_sel_hi:[1,0]
	v_pk_add_f32 v[46:47], v[46:47], 1.0 op_sel_hi:[1,0]
	v_pk_add_f32 v[48:49], v[48:49], 1.0 op_sel_hi:[1,0]
	v_pk_add_f32 v[50:51], v[50:51], 1.0 op_sel_hi:[1,0]
	v_rcp_f32_e32 v46, v46
	v_rcp_f32_e32 v44, v44
	v_rcp_f32_e32 v45, v45
	v_rcp_f32_e32 v47, v47
	v_rcp_f32_e32 v50, v50
	v_rcp_f32_e32 v51, v51
	v_rcp_f32_e32 v48, v48
	v_rcp_f32_e32 v49, v49
	v_add_u32_e32 v52, 0x90, v148
	v_pk_mul_f32 v[34:35], v[38:39], v[34:35]
	v_pk_mul_f32 v[32:33], v[36:37], v[32:33]
	v_mad_i64_i32 v[52:53], s[44:45], v52, s56, v[140:141]
	v_pk_mul_f32 v[36:37], v[44:45], v[34:35]
	v_pk_mul_f32 v[34:35], v[46:47], v[32:33]
	v_pk_mul_f32 v[42:43], v[48:49], v[42:43]
	v_pk_mul_f32 v[40:41], v[50:51], v[40:41]
	v_lshl_add_u64 v[38:39], v[52:53], 0, v[112:113]
	v_cvt_pk_bf16_f32 v32, v40, v41
	v_cvt_pk_bf16_f32 v33, v42, v43
	v_cvt_pk_bf16_f32 v34, v34, v35
	v_cvt_pk_bf16_f32 v35, v36, v37
	global_store_dwordx4 v[38:39], v[32:35], off
	v_pk_mul_f32 v[26:27], v[30:31], v[26:27]
	v_pk_mul_f32 v[24:25], v[28:29], v[24:25]
	v_pk_mul_f32 v[32:33], v[30:31], s[10:11] op_sel_hi:[1,0]
	v_pk_mul_f32 v[34:35], v[28:29], s[10:11] op_sel_hi:[1,0]
	v_pk_mul_f32 v[28:29], v[22:23], s[10:11] op_sel_hi:[1,0]
	v_pk_mul_f32 v[30:31], v[20:21], s[10:11] op_sel_hi:[1,0]
	v_exp_f32_e32 v28, v28
	v_exp_f32_e32 v30, v30
	v_exp_f32_e32 v29, v29
	v_exp_f32_e32 v31, v31
	v_exp_f32_e32 v34, v34
	v_exp_f32_e32 v32, v32
	v_exp_f32_e32 v33, v33
	v_exp_f32_e32 v35, v35
	v_pk_add_f32 v[28:29], v[28:29], 1.0 op_sel_hi:[1,0]
	v_pk_add_f32 v[30:31], v[30:31], 1.0 op_sel_hi:[1,0]
	v_pk_add_f32 v[32:33], v[32:33], 1.0 op_sel_hi:[1,0]
	v_pk_add_f32 v[34:35], v[34:35], 1.0 op_sel_hi:[1,0]
	v_rcp_f32_e32 v30, v30
	v_rcp_f32_e32 v28, v28
	v_rcp_f32_e32 v29, v29
	v_rcp_f32_e32 v31, v31
	v_rcp_f32_e32 v34, v34
	v_rcp_f32_e32 v35, v35
	v_rcp_f32_e32 v32, v32
	v_rcp_f32_e32 v33, v33
	v_add_u32_e32 v36, 0xa0, v148
	v_pk_mul_f32 v[18:19], v[22:23], v[18:19]
	v_pk_mul_f32 v[16:17], v[20:21], v[16:17]
	v_mad_i64_i32 v[36:37], s[44:45], v36, s56, v[140:141]
	v_pk_mul_f32 v[20:21], v[28:29], v[18:19]
	v_pk_mul_f32 v[18:19], v[30:31], v[16:17]
	v_pk_mul_f32 v[26:27], v[32:33], v[26:27]
	v_pk_mul_f32 v[24:25], v[34:35], v[24:25]
	v_lshl_add_u64 v[22:23], v[36:37], 0, v[112:113]
	v_cvt_pk_bf16_f32 v16, v24, v25
	v_cvt_pk_bf16_f32 v17, v26, v27
	v_cvt_pk_bf16_f32 v18, v18, v19
	v_cvt_pk_bf16_f32 v19, v20, v21
	global_store_dwordx4 v[22:23], v[16:19], off
	v_pk_mul_f32 v[10:11], v[14:15], v[10:11]
	v_pk_mul_f32 v[8:9], v[12:13], v[8:9]
	v_pk_mul_f32 v[16:17], v[14:15], s[10:11] op_sel_hi:[1,0]
	v_pk_mul_f32 v[18:19], v[12:13], s[10:11] op_sel_hi:[1,0]
	v_pk_mul_f32 v[12:13], v[6:7], s[10:11] op_sel_hi:[1,0]
	v_pk_mul_f32 v[14:15], v[4:5], s[10:11] op_sel_hi:[1,0]
	v_exp_f32_e32 v12, v12
	v_exp_f32_e32 v14, v14
	v_exp_f32_e32 v13, v13
	v_exp_f32_e32 v15, v15
	v_exp_f32_e32 v18, v18
	v_exp_f32_e32 v16, v16
	v_exp_f32_e32 v17, v17
	v_exp_f32_e32 v19, v19
	v_pk_add_f32 v[12:13], v[12:13], 1.0 op_sel_hi:[1,0]
	v_pk_add_f32 v[14:15], v[14:15], 1.0 op_sel_hi:[1,0]
	v_pk_add_f32 v[16:17], v[16:17], 1.0 op_sel_hi:[1,0]
	v_pk_add_f32 v[18:19], v[18:19], 1.0 op_sel_hi:[1,0]
	v_rcp_f32_e32 v14, v14
	v_rcp_f32_e32 v12, v12
	v_rcp_f32_e32 v13, v13
	v_rcp_f32_e32 v15, v15
	v_rcp_f32_e32 v18, v18
	v_rcp_f32_e32 v19, v19
	v_rcp_f32_e32 v16, v16
	v_rcp_f32_e32 v17, v17
	v_add_u32_e32 v20, 0xb0, v148
	v_mad_i64_i32 v[20:21], s[44:45], v20, s56, v[140:141]
	v_pk_mul_f32 v[2:3], v[6:7], v[2:3]
	v_pk_mul_f32 v[0:1], v[4:5], v[0:1]
	v_pk_mul_f32 v[4:5], v[12:13], v[2:3]
	v_pk_mul_f32 v[2:3], v[14:15], v[0:1]
	v_lshl_add_u64 v[6:7], v[20:21], 0, v[112:113]
	s_andn2_b64 vcc, exec, s[4:5]
	s_mov_b64 s[4:5], -1
	v_pk_mul_f32 v[10:11], v[16:17], v[10:11]
	v_pk_mul_f32 v[8:9], v[18:19], v[8:9]
	v_cvt_pk_bf16_f32 v1, v10, v11
	v_cvt_pk_bf16_f32 v2, v2, v3
	v_cvt_pk_bf16_f32 v3, v4, v5
	s_nop 0
	v_cvt_pk_bf16_f32 v0, v8, v9
	global_store_dwordx4 v[6:7], v[0:3], off
	s_cbranch_vccnz .LBB0_252
	s_andn2_b64 vcc, exec, s[0:1]
	s_cbranch_vccnz .LBB0_251
	s_barrier
	s_branch .LBB0_251

; __device__ __forceinline__ unsigned cvt_pk_bf16(float lo, float hi) { unsigned r; asm("v_cvt_pk_bf16_f32 %0, %1, %2" : "=v"(r) : "v"(lo), "v"(hi)); return r; }
;     __device__ __forceinline__ void operator()(const Acc& acc, const Unit& u, int wr, int wc, int fr, int fq) const {
;         const int row0 = u.pm * 256 + wr * 64 + fr, h0 = u.pn * 128 + wc * 32 + 8 * fq;
; #pragma unroll
;         for (int ai = 0; ai < 2; ++ai)
; #pragma unroll
;             for (int m = 0; m < 4; ++m) { bf16_t* rp = ACT + (size_t)(row0 + ai * 128 + m * 16) * FF + h0; float v[8];
; #pragma unroll
;                 for (int n = 0; n < 2; ++n) { const f32x4 a = acc[ai][0][m][n], b = acc[ai][1][m][n];
;                     const f32x4 t = a * (-LOG2E); f32x4 e; e.x = __builtin_amdgcn_exp2f(t.x); e.y = __builtin_amdgcn_exp2f(t.y); e.z = __builtin_amdgcn_exp2f(t.z); e.w = __builtin_amdgcn_exp2f(t.w);
;                     const f32x4 d = e + 1.0f; f32x4 r; r.x = __builtin_amdgcn_rcpf(d.x); r.y = __builtin_amdgcn_rcpf(d.y); r.z = __builtin_amdgcn_rcpf(d.z); r.w = __builtin_amdgcn_rcpf(d.w);
;                     const f32x4 o = (a * b) * r; v[4 * n + 0] = o.x; v[4 * n + 1] = o.y; v[4 * n + 2] = o.z; v[4 * n + 3] = o.w; }
;                 u32x4 w; w.x = cvt_pk_bf16(v[0], v[1]); w.y = cvt_pk_bf16(v[2], v[3]); w.z = cvt_pk_bf16(v[4], v[5]); w.w = cvt_pk_bf16(v[6], v[7]); __builtin_nontemporal_store(w, (u32x4*)rp); }
.LBB0_1047:
	v_pk_mul_f32 v[152:153], v[126:127], s[22:23] op_sel_hi:[1,0]
	v_pk_mul_f32 v[122:123], v[126:127], v[122:123]
	v_pk_mul_f32 v[126:127], v[116:117], s[22:23] op_sel_hi:[1,0]
	v_pk_mul_f32 v[154:155], v[124:125], s[22:23] op_sel_hi:[1,0]
	v_pk_mul_f32 v[120:121], v[124:125], v[120:121]
	v_pk_mul_f32 v[124:125], v[118:119], s[22:23] op_sel_hi:[1,0]
	v_exp_f32_e32 v126, v126
	v_exp_f32_e32 v127, v127
	v_exp_f32_e32 v154, v154
	v_exp_f32_e32 v152, v152
	v_exp_f32_e32 v153, v153
	v_exp_f32_e32 v155, v155
	v_exp_f32_e32 v124, v124
	v_exp_f32_e32 v125, v125
	v_pk_add_f32 v[126:127], v[126:127], 1.0 op_sel_hi:[1,0]
	v_pk_add_f32 v[152:153], v[152:153], 1.0 op_sel_hi:[1,0]
	v_pk_add_f32 v[154:155], v[154:155], 1.0 op_sel_hi:[1,0]
	v_pk_add_f32 v[124:125], v[124:125], 1.0 op_sel_hi:[1,0]
	v_rcp_f32_e32 v126, v126
	v_rcp_f32_e32 v127, v127
	v_rcp_f32_e32 v154, v154
	v_rcp_f32_e32 v155, v155
	v_rcp_f32_e32 v152, v152
	v_rcp_f32_e32 v153, v153
	v_rcp_f32_e32 v124, v124
	v_rcp_f32_e32 v125, v125
	v_lshl_or_b32 v150, s58, 7, v144
	v_lshl_add_u32 v148, s40, 8, v142
	v_ashrrev_i32_e32 v151, 31, v150
	v_mov_b64_e32 v[140:141], s[14:15]
	v_pk_mul_f32 v[112:113], v[116:117], v[112:113]
	v_mad_i64_i32 v[156:157], s[42:43], v148, s57, v[140:141]
	v_pk_mul_f32 v[114:115], v[118:119], v[114:115]
	v_pk_mul_f32 v[116:117], v[126:127], v[112:113]
	v_lshlrev_b64 v[112:113], 1, v[150:151]
	v_pk_mul_f32 v[122:123], v[152:153], v[122:123]
	v_pk_mul_f32 v[120:121], v[154:155], v[120:121]
	v_pk_mul_f32 v[118:119], v[124:125], v[114:115]
	v_lshl_add_u64 v[124:125], v[156:157], 0, v[112:113]
	v_cvt_pk_bf16_f32 v114, v120, v121
	v_cvt_pk_bf16_f32 v115, v122, v123
	v_cvt_pk_bf16_f32 v116, v116, v117
	v_cvt_pk_bf16_f32 v117, v118, v119
	global_store_dwordx4 v[124:125], v[114:117], off
	v_pk_mul_f32 v[106:107], v[110:111], v[106:107]
	v_pk_mul_f32 v[104:105], v[108:109], v[104:105]
	v_pk_mul_f32 v[114:115], v[110:111], s[22:23] op_sel_hi:[1,0]
	v_pk_mul_f32 v[116:117], v[108:109], s[22:23] op_sel_hi:[1,0]
	v_pk_mul_f32 v[108:109], v[102:103], s[22:23] op_sel_hi:[1,0]
	v_pk_mul_f32 v[110:111], v[100:101], s[22:23] op_sel_hi:[1,0]
	v_exp_f32_e32 v108, v108
	v_exp_f32_e32 v110, v110
	v_exp_f32_e32 v109, v109
	v_exp_f32_e32 v111, v111
	v_exp_f32_e32 v116, v116
	v_exp_f32_e32 v114, v114
	v_exp_f32_e32 v115, v115
	v_exp_f32_e32 v117, v117
	v_pk_add_f32 v[108:109], v[108:109], 1.0 op_sel_hi:[1,0]
	v_pk_add_f32 v[110:111], v[110:111], 1.0 op_sel_hi:[1,0]
	v_pk_add_f32 v[114:115], v[114:115], 1.0 op_sel_hi:[1,0]
	v_pk_add_f32 v[116:117], v[116:117], 1.0 op_sel_hi:[1,0]
	v_rcp_f32_e32 v110, v110
	v_rcp_f32_e32 v108, v108
	v_rcp_f32_e32 v109, v109
	v_rcp_f32_e32 v111, v111
	v_rcp_f32_e32 v116, v116
	v_rcp_f32_e32 v117, v117
	v_rcp_f32_e32 v114, v114
	v_rcp_f32_e32 v115, v115
	v_or_b32_e32 v118, 16, v148
	v_pk_mul_f32 v[98:99], v[102:103], v[98:99]
	v_pk_mul_f32 v[96:97], v[100:101], v[96:97]
	v_mad_i64_i32 v[118:119], s[42:43], v118, s57, v[140:141]
	v_pk_mul_f32 v[100:101], v[108:109], v[98:99]
	v_pk_mul_f32 v[98:99], v[110:111], v[96:97]
	v_pk_mul_f32 v[106:107], v[114:115], v[106:107]
	v_pk_mul_f32 v[104:105], v[116:117], v[104:105]
	v_lshl_add_u64 v[102:103], v[118:119], 0, v[112:113]
	v_cvt_pk_bf16_f32 v96, v104, v105
	v_cvt_pk_bf16_f32 v97, v106, v107
	v_cvt_pk_bf16_f32 v98, v98, v99
	v_cvt_pk_bf16_f32 v99, v100, v101
	global_store_dwordx4 v[102:103], v[96:99], off
	v_pk_mul_f32 v[90:91], v[94:95], v[90:91]
	v_pk_mul_f32 v[88:89], v[92:93], v[88:89]
	v_pk_mul_f32 v[96:97], v[94:95], s[22:23] op_sel_hi:[1,0]
	v_pk_mul_f32 v[98:99], v[92:93], s[22:23] op_sel_hi:[1,0]
	v_pk_mul_f32 v[92:93], v[86:87], s[22:23] op_sel_hi:[1,0]
	v_pk_mul_f32 v[94:95], v[84:85], s[22:23] op_sel_hi:[1,0]
	v_exp_f32_e32 v92, v92
	v_exp_f32_e32 v94, v94
	v_exp_f32_e32 v93, v93
	v_exp_f32_e32 v95, v95
	v_exp_f32_e32 v98, v98
	v_exp_f32_e32 v96, v96
	v_exp_f32_e32 v97, v97
	v_exp_f32_e32 v99, v99
	v_pk_add_f32 v[92:93], v[92:93], 1.0 op_sel_hi:[1,0]
	v_pk_add_f32 v[94:95], v[94:95], 1.0 op_sel_hi:[1,0]
	v_pk_add_f32 v[96:97], v[96:97], 1.0 op_sel_hi:[1,0]
	v_pk_add_f32 v[98:99], v[98:99], 1.0 op_sel_hi:[1,0]
	v_rcp_f32_e32 v94, v94
	v_rcp_f32_e32 v92, v92
	v_rcp_f32_e32 v93, v93
	v_rcp_f32_e32 v95, v95
	v_rcp_f32_e32 v98, v98
	v_rcp_f32_e32 v99, v99
	v_rcp_f32_e32 v96, v96
	v_rcp_f32_e32 v97, v97
	v_or_b32_e32 v100, 32, v148
	v_pk_mul_f32 v[82:83], v[86:87], v[82:83]
	v_pk_mul_f32 v[80:81], v[84:85], v[80:81]
	v_mad_i64_i32 v[100:101], s[42:43], v100, s57, v[140:141]
	v_pk_mul_f32 v[84:85], v[92:93], v[82:83]
	v_pk_mul_f32 v[82:83], v[94:95], v[80:81]
	v_pk_mul_f32 v[90:91], v[96:97], v[90:91]
	v_pk_mul_f32 v[88:89], v[98:99], v[88:89]
	v_lshl_add_u64 v[86:87], v[100:101], 0, v[112:113]
	v_cvt_pk_bf16_f32 v80, v88, v89
	v_cvt_pk_bf16_f32 v81, v90, v91
	v_cvt_pk_bf16_f32 v82, v82, v83
	v_cvt_pk_bf16_f32 v83, v84, v85
	global_store_dwordx4 v[86:87], v[80:83], off
	v_pk_mul_f32 v[74:75], v[78:79], v[74:75]
	v_pk_mul_f32 v[72:73], v[76:77], v[72:73]
	v_pk_mul_f32 v[80:81], v[78:79], s[22:23] op_sel_hi:[1,0]
	v_pk_mul_f32 v[82:83], v[76:77], s[22:23] op_sel_hi:[1,0]
	v_pk_mul_f32 v[76:77], v[70:71], s[22:23] op_sel_hi:[1,0]
	v_pk_mul_f32 v[78:79], v[68:69], s[22:23] op_sel_hi:[1,0]
	v_exp_f32_e32 v76, v76
	v_exp_f32_e32 v78, v78
	v_exp_f32_e32 v77, v77
	v_exp_f32_e32 v79, v79
	v_exp_f32_e32 v82, v82
	v_exp_f32_e32 v80, v80
	v_exp_f32_e32 v81, v81
	v_exp_f32_e32 v83, v83
	v_pk_add_f32 v[76:77], v[76:77], 1.0 op_sel_hi:[1,0]
	v_pk_add_f32 v[78:79], v[78:79], 1.0 op_sel_hi:[1,0]
	v_pk_add_f32 v[80:81], v[80:81], 1.0 op_sel_hi:[1,0]
	v_pk_add_f32 v[82:83], v[82:83], 1.0 op_sel_hi:[1,0]
	v_rcp_f32_e32 v78, v78
; __device__ __forceinline__ unsigned cvt_pk_bf16(float lo, float hi) { unsigned r; asm("v_cvt_pk_bf16_f32 %0, %1, %2" : "=v"(r) : "v"(lo), "v"(hi)); return r; }
;     __device__ __forceinline__ void operator()(const Acc& acc, const Unit& u, int wr, int wc, int fr, int fq) const {
;         const int row0 = u.pm * 256 + wr * 64 + fr, h0 = u.pn * 128 + wc * 32 + 8 * fq;
; #pragma unroll
;         for (int ai = 0; ai < 2; ++ai)
; #pragma unroll
;             for (int m = 0; m < 4; ++m) { bf16_t* rp = ACT + (size_t)(row0 + ai * 128 + m * 16) * FF + h0; float v[8];
; #pragma unroll
;                 for (int n = 0; n < 2; ++n) { const f32x4 a = acc[ai][0][m][n], b = acc[ai][1][m][n];
;                     const f32x4 t = a * (-LOG2E); f32x4 e; e.x = __builtin_amdgcn_exp2f(t.x); e.y = __builtin_amdgcn_exp2f(t.y); e.z = __builtin_amdgcn_exp2f(t.z); e.w = __builtin_amdgcn_exp2f(t.w);
;                     const f32x4 d = e + 1.0f; f32x4 r; r.x = __builtin_amdgcn_rcpf(d.x); r.y = __builtin_amdgcn_rcpf(d.y); r.z = __builtin_amdgcn_rcpf(d.z); r.w = __builtin_amdgcn_rcpf(d.w);
;                     const f32x4 o = (a * b) * r; v[4 * n + 0] = o.x; v[4 * n + 1] = o.y; v[4 * n + 2] = o.z; v[4 * n + 3] = o.w; }
;                 u32x4 w; w.x = cvt_pk_bf16(v[0], v[1]); w.y = cvt_pk_bf16(v[2], v[3]); w.z = cvt_pk_bf16(v[4], v[5]); w.w = cvt_pk_bf16(v[6], v[7]); __builtin_nontemporal_store(w, (u32x4*)rp); }
	v_rcp_f32_e32 v76, v76
	v_rcp_f32_e32 v77, v77
	v_rcp_f32_e32 v79, v79
	v_rcp_f32_e32 v82, v82
	v_rcp_f32_e32 v83, v83
	v_rcp_f32_e32 v80, v80
	v_rcp_f32_e32 v81, v81
	v_or_b32_e32 v84, 48, v148
	v_pk_mul_f32 v[66:67], v[70:71], v[66:67]
	v_pk_mul_f32 v[64:65], v[68:69], v[64:65]
	v_mad_i64_i32 v[84:85], s[42:43], v84, s57, v[140:141]
	v_pk_mul_f32 v[68:69], v[76:77], v[66:67]
	v_pk_mul_f32 v[66:67], v[78:79], v[64:65]
	v_pk_mul_f32 v[74:75], v[80:81], v[74:75]
	v_pk_mul_f32 v[72:73], v[82:83], v[72:73]
	v_lshl_add_u64 v[70:71], v[84:85], 0, v[112:113]
	v_cvt_pk_bf16_f32 v64, v72, v73
	v_cvt_pk_bf16_f32 v65, v74, v75
	v_cvt_pk_bf16_f32 v66, v66, v67
	v_cvt_pk_bf16_f32 v67, v68, v69
	global_store_dwordx4 v[70:71], v[64:67], off
	v_pk_mul_f32 v[58:59], v[62:63], v[58:59]
	v_pk_mul_f32 v[56:57], v[60:61], v[56:57]
	v_pk_mul_f32 v[64:65], v[62:63], s[22:23] op_sel_hi:[1,0]
	v_pk_mul_f32 v[66:67], v[60:61], s[22:23] op_sel_hi:[1,0]
	v_pk_mul_f32 v[60:61], v[54:55], s[22:23] op_sel_hi:[1,0]
	v_pk_mul_f32 v[62:63], v[52:53], s[22:23] op_sel_hi:[1,0]
	v_exp_f32_e32 v60, v60
	v_exp_f32_e32 v62, v62
	v_exp_f32_e32 v61, v61
	v_exp_f32_e32 v63, v63
	v_exp_f32_e32 v66, v66
	v_exp_f32_e32 v64, v64
	v_exp_f32_e32 v65, v65
	v_exp_f32_e32 v67, v67
	v_pk_add_f32 v[60:61], v[60:61], 1.0 op_sel_hi:[1,0]
	v_pk_add_f32 v[62:63], v[62:63], 1.0 op_sel_hi:[1,0]
	v_pk_add_f32 v[64:65], v[64:65], 1.0 op_sel_hi:[1,0]
	v_pk_add_f32 v[66:67], v[66:67], 1.0 op_sel_hi:[1,0]
	v_rcp_f32_e32 v62, v62
	v_rcp_f32_e32 v60, v60
	v_rcp_f32_e32 v61, v61
	v_rcp_f32_e32 v63, v63
	v_rcp_f32_e32 v66, v66
	v_rcp_f32_e32 v67, v67
	v_rcp_f32_e32 v64, v64
	v_rcp_f32_e32 v65, v65
	v_add_u32_e32 v68, 0x80, v148
	v_pk_mul_f32 v[50:51], v[54:55], v[50:51]
	v_pk_mul_f32 v[48:49], v[52:53], v[48:49]
	v_mad_i64_i32 v[68:69], s[42:43], v68, s57, v[140:141]
	v_pk_mul_f32 v[52:53], v[60:61], v[50:51]
	v_pk_mul_f32 v[50:51], v[62:63], v[48:49]
	v_pk_mul_f32 v[58:59], v[64:65], v[58:59]
	v_pk_mul_f32 v[56:57], v[66:67], v[56:57]
	v_lshl_add_u64 v[54:55], v[68:69], 0, v[112:113]
	v_cvt_pk_bf16_f32 v48, v56, v57
	v_cvt_pk_bf16_f32 v49, v58, v59
	v_cvt_pk_bf16_f32 v50, v50, v51
	v_cvt_pk_bf16_f32 v51, v52, v53
	global_store_dwordx4 v[54:55], v[48:51], off
	v_pk_mul_f32 v[42:43], v[46:47], v[42:43]
	v_pk_mul_f32 v[40:41], v[44:45], v[40:41]
	v_pk_mul_f32 v[48:49], v[46:47], s[22:23] op_sel_hi:[1,0]
	v_pk_mul_f32 v[50:51], v[44:45], s[22:23] op_sel_hi:[1,0]
	v_pk_mul_f32 v[44:45], v[38:39], s[22:23] op_sel_hi:[1,0]
	v_pk_mul_f32 v[46:47], v[36:37], s[22:23] op_sel_hi:[1,0]
	v_exp_f32_e32 v44, v44
	v_exp_f32_e32 v46, v46
	v_exp_f32_e32 v45, v45
	v_exp_f32_e32 v47, v47
	v_exp_f32_e32 v50, v50
	v_exp_f32_e32 v48, v48
	v_exp_f32_e32 v49, v49
	v_exp_f32_e32 v51, v51
	v_pk_add_f32 v[44:45], v[44:45], 1.0 op_sel_hi:[1,0]
	v_pk_add_f32 v[46:47], v[46:47], 1.0 op_sel_hi:[1,0]
	v_pk_add_f32 v[48:49], v[48:49], 1.0 op_sel_hi:[1,0]
	v_pk_add_f32 v[50:51], v[50:51], 1.0 op_sel_hi:[1,0]
	v_rcp_f32_e32 v46, v46
	v_rcp_f32_e32 v44, v44
	v_rcp_f32_e32 v45, v45
	v_rcp_f32_e32 v47, v47
	v_rcp_f32_e32 v50, v50
	v_rcp_f32_e32 v51, v51
	v_rcp_f32_e32 v48, v48
	v_rcp_f32_e32 v49, v49
	v_add_u32_e32 v52, 0x90, v148
	v_pk_mul_f32 v[34:35], v[38:39], v[34:35]
	v_pk_mul_f32 v[32:33], v[36:37], v[32:33]
	v_mad_i64_i32 v[52:53], s[42:43], v52, s57, v[140:141]
	v_pk_mul_f32 v[36:37], v[44:45], v[34:35]
	v_pk_mul_f32 v[34:35], v[46:47], v[32:33]
	v_pk_mul_f32 v[42:43], v[48:49], v[42:43]
	v_pk_mul_f32 v[40:41], v[50:51], v[40:41]
	v_lshl_add_u64 v[38:39], v[52:53], 0, v[112:113]
	v_cvt_pk_bf16_f32 v32, v40, v41
	v_cvt_pk_bf16_f32 v33, v42, v43
	v_cvt_pk_bf16_f32 v34, v34, v35
	v_cvt_pk_bf16_f32 v35, v36, v37
	global_store_dwordx4 v[38:39], v[32:35], off
	v_pk_mul_f32 v[26:27], v[30:31], v[26:27]
	v_pk_mul_f32 v[24:25], v[28:29], v[24:25]
	v_pk_mul_f32 v[32:33], v[30:31], s[22:23] op_sel_hi:[1,0]
	v_pk_mul_f32 v[34:35], v[28:29], s[22:23] op_sel_hi:[1,0]
	v_pk_mul_f32 v[28:29], v[22:23], s[22:23] op_sel_hi:[1,0]
	v_pk_mul_f32 v[30:31], v[20:21], s[22:23] op_sel_hi:[1,0]
	v_exp_f32_e32 v28, v28
	v_exp_f32_e32 v30, v30
	v_exp_f32_e32 v29, v29
	v_exp_f32_e32 v31, v31
	v_exp_f32_e32 v34, v34
	v_exp_f32_e32 v32, v32
	v_exp_f32_e32 v33, v33
	v_exp_f32_e32 v35, v35
	v_pk_add_f32 v[28:29], v[28:29], 1.0 op_sel_hi:[1,0]
	v_pk_add_f32 v[30:31], v[30:31], 1.0 op_sel_hi:[1,0]
	v_pk_add_f32 v[32:33], v[32:33], 1.0 op_sel_hi:[1,0]
	v_pk_add_f32 v[34:35], v[34:35], 1.0 op_sel_hi:[1,0]
	v_rcp_f32_e32 v30, v30
	v_rcp_f32_e32 v28, v28
	v_rcp_f32_e32 v29, v29
	v_rcp_f32_e32 v31, v31
	v_rcp_f32_e32 v34, v34
	v_rcp_f32_e32 v35, v35
	v_rcp_f32_e32 v32, v32
	v_rcp_f32_e32 v33, v33
	v_add_u32_e32 v36, 0xa0, v148
	v_pk_mul_f32 v[18:19], v[22:23], v[18:19]
	v_pk_mul_f32 v[16:17], v[20:21], v[16:17]
	v_mad_i64_i32 v[36:37], s[42:43], v36, s57, v[140:141]
	v_pk_mul_f32 v[20:21], v[28:29], v[18:19]
	v_pk_mul_f32 v[18:19], v[30:31], v[16:17]
	v_pk_mul_f32 v[26:27], v[32:33], v[26:27]
	v_pk_mul_f32 v[24:25], v[34:35], v[24:25]
	v_lshl_add_u64 v[22:23], v[36:37], 0, v[112:113]
	v_cvt_pk_bf16_f32 v16, v24, v25
	v_cvt_pk_bf16_f32 v17, v26, v27
	v_cvt_pk_bf16_f32 v18, v18, v19
	v_cvt_pk_bf16_f32 v19, v20, v21
	global_store_dwordx4 v[22:23], v[16:19], off
	v_pk_mul_f32 v[10:11], v[14:15], v[10:11]
	v_pk_mul_f32 v[8:9], v[12:13], v[8:9]
	v_pk_mul_f32 v[16:17], v[14:15], s[22:23] op_sel_hi:[1,0]
	v_pk_mul_f32 v[18:19], v[12:13], s[22:23] op_sel_hi:[1,0]
	v_pk_mul_f32 v[12:13], v[6:7], s[22:23] op_sel_hi:[1,0]
	v_pk_mul_f32 v[14:15], v[4:5], s[22:23] op_sel_hi:[1,0]
	v_exp_f32_e32 v12, v12
	v_exp_f32_e32 v14, v14
	v_exp_f32_e32 v13, v13
	v_exp_f32_e32 v15, v15
	v_exp_f32_e32 v18, v18
	v_exp_f32_e32 v16, v16
	v_exp_f32_e32 v17, v17
	v_exp_f32_e32 v19, v19
	v_pk_add_f32 v[12:13], v[12:13], 1.0 op_sel_hi:[1,0]
	v_pk_add_f32 v[14:15], v[14:15], 1.0 op_sel_hi:[1,0]
	v_pk_add_f32 v[16:17], v[16:17], 1.0 op_sel_hi:[1,0]
	v_pk_add_f32 v[18:19], v[18:19], 1.0 op_sel_hi:[1,0]
	v_rcp_f32_e32 v14, v14
	v_rcp_f32_e32 v12, v12
	v_rcp_f32_e32 v13, v13
	v_rcp_f32_e32 v15, v15
	v_rcp_f32_e32 v18, v18
	v_rcp_f32_e32 v19, v19
	v_rcp_f32_e32 v16, v16
	v_rcp_f32_e32 v17, v17
	v_add_u32_e32 v20, 0xb0, v148
	v_mad_i64_i32 v[20:21], s[42:43], v20, s57, v[140:141]
	v_pk_mul_f32 v[2:3], v[6:7], v[2:3]
	v_pk_mul_f32 v[0:1], v[4:5], v[0:1]
	v_pk_mul_f32 v[4:5], v[12:13], v[2:3]
	v_pk_mul_f32 v[2:3], v[14:15], v[0:1]
	v_lshl_add_u64 v[6:7], v[20:21], 0, v[112:113]
	s_andn2_b64 vcc, exec, s[4:5]
	s_mov_b64 s[4:5], -1
	v_pk_mul_f32 v[10:11], v[16:17], v[10:11]
	v_pk_mul_f32 v[8:9], v[18:19], v[8:9]
	v_cvt_pk_bf16_f32 v1, v10, v11
	v_cvt_pk_bf16_f32 v2, v2, v3
	v_cvt_pk_bf16_f32 v3, v4, v5
	s_nop 0
	v_cvt_pk_bf16_f32 v0, v8, v9
	global_store_dwordx4 v[6:7], v[0:3], off
	s_cbranch_vccnz .LBB0_1040
	s_andn2_b64 vcc, exec, s[6:7]
	s_cbranch_vccnz .LBB0_1039
	s_barrier
	s_branch .LBB0_1039

; __device__ __forceinline__ unsigned cvt_pk_bf16(float lo, float hi) { unsigned r; asm("v_cvt_pk_bf16_f32 %0, %1, %2" : "=v"(r) : "v"(lo), "v"(hi)); return r; }
;     __device__ __forceinline__ void operator()(const Acc& acc, const Unit& u, int wr, int wc, int fr, int fq) const {
;         const int row0 = u.pm * 256 + wr * 64 + fr, h0 = u.pn * 128 + wc * 32 + 8 * fq;
; #pragma unroll
;         for (int ai = 0; ai < 2; ++ai)
; #pragma unroll
;             for (int m = 0; m < 4; ++m) { bf16_t* rp = ACT + (size_t)(row0 + ai * 128 + m * 16) * FF + h0; float v[8];
; #pragma unroll
;                 for (int n = 0; n < 2; ++n) { const f32x4 a = acc[ai][0][m][n], b = acc[ai][1][m][n];
;                     const f32x4 t = a * (-LOG2E); f32x4 e; e.x = __builtin_amdgcn_exp2f(t.x); e.y = __builtin_amdgcn_exp2f(t.y); e.z = __builtin_amdgcn_exp2f(t.z); e.w = __builtin_amdgcn_exp2f(t.w);
;                     const f32x4 d = e + 1.0f; f32x4 r; r.x = __builtin_amdgcn_rcpf(d.x); r.y = __builtin_amdgcn_rcpf(d.y); r.z = __builtin_amdgcn_rcpf(d.z); r.w = __builtin_amdgcn_rcpf(d.w);
;                     const f32x4 o = (a * b) * r; v[4 * n + 0] = o.x; v[4 * n + 1] = o.y; v[4 * n + 2] = o.z; v[4 * n + 3] = o.w; }
;                 u32x4 w; w.x = cvt_pk_bf16(v[0], v[1]); w.y = cvt_pk_bf16(v[2], v[3]); w.z = cvt_pk_bf16(v[4], v[5]); w.w = cvt_pk_bf16(v[6], v[7]); __builtin_nontemporal_store(w, (u32x4*)rp); }
.LBB0_1250:
	v_pk_mul_f32 v[152:153], v[126:127], s[22:23] op_sel_hi:[1,0]
	v_pk_mul_f32 v[122:123], v[126:127], v[122:123]
	v_pk_mul_f32 v[126:127], v[116:117], s[22:23] op_sel_hi:[1,0]
	v_pk_mul_f32 v[154:155], v[124:125], s[22:23] op_sel_hi:[1,0]
	v_pk_mul_f32 v[120:121], v[124:125], v[120:121]
	v_pk_mul_f32 v[124:125], v[118:119], s[22:23] op_sel_hi:[1,0]
	v_exp_f32_e32 v126, v126
	v_exp_f32_e32 v127, v127
	v_exp_f32_e32 v154, v154
	v_exp_f32_e32 v152, v152
	v_exp_f32_e32 v153, v153
	v_exp_f32_e32 v155, v155
	v_exp_f32_e32 v124, v124
	v_exp_f32_e32 v125, v125
	v_pk_add_f32 v[126:127], v[126:127], 1.0 op_sel_hi:[1,0]
	v_pk_add_f32 v[152:153], v[152:153], 1.0 op_sel_hi:[1,0]
	v_pk_add_f32 v[154:155], v[154:155], 1.0 op_sel_hi:[1,0]
	v_pk_add_f32 v[124:125], v[124:125], 1.0 op_sel_hi:[1,0]
	v_rcp_f32_e32 v126, v126
	v_rcp_f32_e32 v127, v127
	v_rcp_f32_e32 v154, v154
	v_rcp_f32_e32 v155, v155
	v_rcp_f32_e32 v152, v152
	v_rcp_f32_e32 v153, v153
	v_rcp_f32_e32 v124, v124
	v_rcp_f32_e32 v125, v125
	v_lshl_or_b32 v150, s58, 7, v144
	v_lshl_add_u32 v148, s40, 8, v142
	v_ashrrev_i32_e32 v151, 31, v150
	v_mov_b64_e32 v[140:141], s[14:15]
	v_pk_mul_f32 v[112:113], v[116:117], v[112:113]
	v_mad_i64_i32 v[156:157], s[42:43], v148, s57, v[140:141]
	v_pk_mul_f32 v[114:115], v[118:119], v[114:115]
	v_pk_mul_f32 v[116:117], v[126:127], v[112:113]
	v_lshlrev_b64 v[112:113], 1, v[150:151]
	v_pk_mul_f32 v[122:123], v[152:153], v[122:123]
	v_pk_mul_f32 v[120:121], v[154:155], v[120:121]
	v_pk_mul_f32 v[118:119], v[124:125], v[114:115]
	v_lshl_add_u64 v[124:125], v[156:157], 0, v[112:113]
	v_cvt_pk_bf16_f32 v114, v120, v121
	v_cvt_pk_bf16_f32 v115, v122, v123
	v_cvt_pk_bf16_f32 v116, v116, v117
	v_cvt_pk_bf16_f32 v117, v118, v119
	global_store_dwordx4 v[124:125], v[114:117], off
	v_pk_mul_f32 v[106:107], v[110:111], v[106:107]
	v_pk_mul_f32 v[104:105], v[108:109], v[104:105]
	v_pk_mul_f32 v[114:115], v[110:111], s[22:23] op_sel_hi:[1,0]
	v_pk_mul_f32 v[116:117], v[108:109], s[22:23] op_sel_hi:[1,0]
	v_pk_mul_f32 v[108:109], v[102:103], s[22:23] op_sel_hi:[1,0]
	v_pk_mul_f32 v[110:111], v[100:101], s[22:23] op_sel_hi:[1,0]
	v_exp_f32_e32 v108, v108
	v_exp_f32_e32 v110, v110
	v_exp_f32_e32 v109, v109
	v_exp_f32_e32 v111, v111
	v_exp_f32_e32 v116, v116
	v_exp_f32_e32 v114, v114
	v_exp_f32_e32 v115, v115
	v_exp_f32_e32 v117, v117
	v_pk_add_f32 v[108:109], v[108:109], 1.0 op_sel_hi:[1,0]
	v_pk_add_f32 v[110:111], v[110:111], 1.0 op_sel_hi:[1,0]
	v_pk_add_f32 v[114:115], v[114:115], 1.0 op_sel_hi:[1,0]
	v_pk_add_f32 v[116:117], v[116:117], 1.0 op_sel_hi:[1,0]
	v_rcp_f32_e32 v110, v110
	v_rcp_f32_e32 v108, v108
	v_rcp_f32_e32 v109, v109
	v_rcp_f32_e32 v111, v111
	v_rcp_f32_e32 v116, v116
	v_rcp_f32_e32 v117, v117
	v_rcp_f32_e32 v114, v114
	v_rcp_f32_e32 v115, v115
	v_or_b32_e32 v118, 16, v148
	v_pk_mul_f32 v[98:99], v[102:103], v[98:99]
	v_pk_mul_f32 v[96:97], v[100:101], v[96:97]
	v_mad_i64_i32 v[118:119], s[42:43], v118, s57, v[140:141]
	v_pk_mul_f32 v[100:101], v[108:109], v[98:99]
	v_pk_mul_f32 v[98:99], v[110:111], v[96:97]
	v_pk_mul_f32 v[106:107], v[114:115], v[106:107]
	v_pk_mul_f32 v[104:105], v[116:117], v[104:105]
	v_lshl_add_u64 v[102:103], v[118:119], 0, v[112:113]
	v_cvt_pk_bf16_f32 v96, v104, v105
	v_cvt_pk_bf16_f32 v97, v106, v107
	v_cvt_pk_bf16_f32 v98, v98, v99
	v_cvt_pk_bf16_f32 v99, v100, v101
	global_store_dwordx4 v[102:103], v[96:99], off
	v_pk_mul_f32 v[90:91], v[94:95], v[90:91]
	v_pk_mul_f32 v[88:89], v[92:93], v[88:89]
	v_pk_mul_f32 v[96:97], v[94:95], s[22:23] op_sel_hi:[1,0]
	v_pk_mul_f32 v[98:99], v[92:93], s[22:23] op_sel_hi:[1,0]
	v_pk_mul_f32 v[92:93], v[86:87], s[22:23] op_sel_hi:[1,0]
	v_pk_mul_f32 v[94:95], v[84:85], s[22:23] op_sel_hi:[1,0]
	v_exp_f32_e32 v92, v92
	v_exp_f32_e32 v94, v94
	v_exp_f32_e32 v93, v93
	v_exp_f32_e32 v95, v95
	v_exp_f32_e32 v98, v98
	v_exp_f32_e32 v96, v96
	v_exp_f32_e32 v97, v97
	v_exp_f32_e32 v99, v99
	v_pk_add_f32 v[92:93], v[92:93], 1.0 op_sel_hi:[1,0]
	v_pk_add_f32 v[94:95], v[94:95], 1.0 op_sel_hi:[1,0]
	v_pk_add_f32 v[96:97], v[96:97], 1.0 op_sel_hi:[1,0]
	v_pk_add_f32 v[98:99], v[98:99], 1.0 op_sel_hi:[1,0]
	v_rcp_f32_e32 v94, v94
	v_rcp_f32_e32 v92, v92
	v_rcp_f32_e32 v93, v93
	v_rcp_f32_e32 v95, v95
	v_rcp_f32_e32 v98, v98
	v_rcp_f32_e32 v99, v99
	v_rcp_f32_e32 v96, v96
	v_rcp_f32_e32 v97, v97
	v_or_b32_e32 v100, 32, v148
	v_pk_mul_f32 v[82:83], v[86:87], v[82:83]
	v_pk_mul_f32 v[80:81], v[84:85], v[80:81]
	v_mad_i64_i32 v[100:101], s[42:43], v100, s57, v[140:141]
	v_pk_mul_f32 v[84:85], v[92:93], v[82:83]
	v_pk_mul_f32 v[82:83], v[94:95], v[80:81]
	v_pk_mul_f32 v[90:91], v[96:97], v[90:91]
	v_pk_mul_f32 v[88:89], v[98:99], v[88:89]
	v_lshl_add_u64 v[86:87], v[100:101], 0, v[112:113]
	v_cvt_pk_bf16_f32 v80, v88, v89
	v_cvt_pk_bf16_f32 v81, v90, v91
	v_cvt_pk_bf16_f32 v82, v82, v83
	v_cvt_pk_bf16_f32 v83, v84, v85
	global_store_dwordx4 v[86:87], v[80:83], off
	v_pk_mul_f32 v[74:75], v[78:79], v[74:75]
	v_pk_mul_f32 v[72:73], v[76:77], v[72:73]
	v_pk_mul_f32 v[80:81], v[78:79], s[22:23] op_sel_hi:[1,0]
	v_pk_mul_f32 v[82:83], v[76:77], s[22:23] op_sel_hi:[1,0]
	v_pk_mul_f32 v[76:77], v[70:71], s[22:23] op_sel_hi:[1,0]
	v_pk_mul_f32 v[78:79], v[68:69], s[22:23] op_sel_hi:[1,0]
	v_exp_f32_e32 v76, v76
	v_exp_f32_e32 v78, v78
	v_exp_f32_e32 v77, v77
	v_exp_f32_e32 v79, v79
	v_exp_f32_e32 v82, v82
	v_exp_f32_e32 v80, v80
	v_exp_f32_e32 v81, v81
	v_exp_f32_e32 v83, v83
	v_pk_add_f32 v[76:77], v[76:77], 1.0 op_sel_hi:[1,0]
	v_pk_add_f32 v[78:79], v[78:79], 1.0 op_sel_hi:[1,0]
	v_pk_add_f32 v[80:81], v[80:81], 1.0 op_sel_hi:[1,0]
	v_pk_add_f32 v[82:83], v[82:83], 1.0 op_sel_hi:[1,0]
	v_rcp_f32_e32 v78, v78
; __device__ __forceinline__ unsigned cvt_pk_bf16(float lo, float hi) { unsigned r; asm("v_cvt_pk_bf16_f32 %0, %1, %2" : "=v"(r) : "v"(lo), "v"(hi)); return r; }
;     __device__ __forceinline__ void operator()(const Acc& acc, const Unit& u, int wr, int wc, int fr, int fq) const {
;         const int row0 = u.pm * 256 + wr * 64 + fr, h0 = u.pn * 128 + wc * 32 + 8 * fq;
; #pragma unroll
;         for (int ai = 0; ai < 2; ++ai)
; #pragma unroll
;             for (int m = 0; m < 4; ++m) { bf16_t* rp = ACT + (size_t)(row0 + ai * 128 + m * 16) * FF + h0; float v[8];
; #pragma unroll
;                 for (int n = 0; n < 2; ++n) { const f32x4 a = acc[ai][0][m][n], b = acc[ai][1][m][n];
;                     const f32x4 t = a * (-LOG2E); f32x4 e; e.x = __builtin_amdgcn_exp2f(t.x); e.y = __builtin_amdgcn_exp2f(t.y); e.z = __builtin_amdgcn_exp2f(t.z); e.w = __builtin_amdgcn_exp2f(t.w);
;                     const f32x4 d = e + 1.0f; f32x4 r; r.x = __builtin_amdgcn_rcpf(d.x); r.y = __builtin_amdgcn_rcpf(d.y); r.z = __builtin_amdgcn_rcpf(d.z); r.w = __builtin_amdgcn_rcpf(d.w);
;                     const f32x4 o = (a * b) * r; v[4 * n + 0] = o.x; v[4 * n + 1] = o.y; v[4 * n + 2] = o.z; v[4 * n + 3] = o.w; }
;                 u32x4 w; w.x = cvt_pk_bf16(v[0], v[1]); w.y = cvt_pk_bf16(v[2], v[3]); w.z = cvt_pk_bf16(v[4], v[5]); w.w = cvt_pk_bf16(v[6], v[7]); __builtin_nontemporal_store(w, (u32x4*)rp); }
	v_rcp_f32_e32 v76, v76
	v_rcp_f32_e32 v77, v77
	v_rcp_f32_e32 v79, v79
	v_rcp_f32_e32 v82, v82
	v_rcp_f32_e32 v83, v83
	v_rcp_f32_e32 v80, v80
	v_rcp_f32_e32 v81, v81
	v_or_b32_e32 v84, 48, v148
	v_pk_mul_f32 v[66:67], v[70:71], v[66:67]
	v_pk_mul_f32 v[64:65], v[68:69], v[64:65]
	v_mad_i64_i32 v[84:85], s[42:43], v84, s57, v[140:141]
	v_pk_mul_f32 v[68:69], v[76:77], v[66:67]
	v_pk_mul_f32 v[66:67], v[78:79], v[64:65]
	v_pk_mul_f32 v[74:75], v[80:81], v[74:75]
	v_pk_mul_f32 v[72:73], v[82:83], v[72:73]
	v_lshl_add_u64 v[70:71], v[84:85], 0, v[112:113]
	v_cvt_pk_bf16_f32 v64, v72, v73
	v_cvt_pk_bf16_f32 v65, v74, v75
	v_cvt_pk_bf16_f32 v66, v66, v67
	v_cvt_pk_bf16_f32 v67, v68, v69
	global_store_dwordx4 v[70:71], v[64:67], off
	v_pk_mul_f32 v[58:59], v[62:63], v[58:59]
	v_pk_mul_f32 v[56:57], v[60:61], v[56:57]
	v_pk_mul_f32 v[64:65], v[62:63], s[22:23] op_sel_hi:[1,0]
	v_pk_mul_f32 v[66:67], v[60:61], s[22:23] op_sel_hi:[1,0]
	v_pk_mul_f32 v[60:61], v[54:55], s[22:23] op_sel_hi:[1,0]
	v_pk_mul_f32 v[62:63], v[52:53], s[22:23] op_sel_hi:[1,0]
	v_exp_f32_e32 v60, v60
	v_exp_f32_e32 v62, v62
	v_exp_f32_e32 v61, v61
	v_exp_f32_e32 v63, v63
	v_exp_f32_e32 v66, v66
	v_exp_f32_e32 v64, v64
	v_exp_f32_e32 v65, v65
	v_exp_f32_e32 v67, v67
	v_pk_add_f32 v[60:61], v[60:61], 1.0 op_sel_hi:[1,0]
	v_pk_add_f32 v[62:63], v[62:63], 1.0 op_sel_hi:[1,0]
	v_pk_add_f32 v[64:65], v[64:65], 1.0 op_sel_hi:[1,0]
	v_pk_add_f32 v[66:67], v[66:67], 1.0 op_sel_hi:[1,0]
	v_rcp_f32_e32 v62, v62
	v_rcp_f32_e32 v60, v60
	v_rcp_f32_e32 v61, v61
	v_rcp_f32_e32 v63, v63
	v_rcp_f32_e32 v66, v66
	v_rcp_f32_e32 v67, v67
	v_rcp_f32_e32 v64, v64
	v_rcp_f32_e32 v65, v65
	v_add_u32_e32 v68, 0x80, v148
	v_pk_mul_f32 v[50:51], v[54:55], v[50:51]
	v_pk_mul_f32 v[48:49], v[52:53], v[48:49]
	v_mad_i64_i32 v[68:69], s[42:43], v68, s57, v[140:141]
	v_pk_mul_f32 v[52:53], v[60:61], v[50:51]
	v_pk_mul_f32 v[50:51], v[62:63], v[48:49]
	v_pk_mul_f32 v[58:59], v[64:65], v[58:59]
	v_pk_mul_f32 v[56:57], v[66:67], v[56:57]
	v_lshl_add_u64 v[54:55], v[68:69], 0, v[112:113]
	v_cvt_pk_bf16_f32 v48, v56, v57
	v_cvt_pk_bf16_f32 v49, v58, v59
	v_cvt_pk_bf16_f32 v50, v50, v51
	v_cvt_pk_bf16_f32 v51, v52, v53
	global_store_dwordx4 v[54:55], v[48:51], off
	v_pk_mul_f32 v[42:43], v[46:47], v[42:43]
	v_pk_mul_f32 v[40:41], v[44:45], v[40:41]
	v_pk_mul_f32 v[48:49], v[46:47], s[22:23] op_sel_hi:[1,0]
	v_pk_mul_f32 v[50:51], v[44:45], s[22:23] op_sel_hi:[1,0]
	v_pk_mul_f32 v[44:45], v[38:39], s[22:23] op_sel_hi:[1,0]
	v_pk_mul_f32 v[46:47], v[36:37], s[22:23] op_sel_hi:[1,0]
	v_exp_f32_e32 v44, v44
	v_exp_f32_e32 v46, v46
	v_exp_f32_e32 v45, v45
	v_exp_f32_e32 v47, v47
	v_exp_f32_e32 v50, v50
	v_exp_f32_e32 v48, v48
	v_exp_f32_e32 v49, v49
	v_exp_f32_e32 v51, v51
	v_pk_add_f32 v[44:45], v[44:45], 1.0 op_sel_hi:[1,0]
	v_pk_add_f32 v[46:47], v[46:47], 1.0 op_sel_hi:[1,0]
	v_pk_add_f32 v[48:49], v[48:49], 1.0 op_sel_hi:[1,0]
	v_pk_add_f32 v[50:51], v[50:51], 1.0 op_sel_hi:[1,0]
	v_rcp_f32_e32 v46, v46
	v_rcp_f32_e32 v44, v44
	v_rcp_f32_e32 v45, v45
	v_rcp_f32_e32 v47, v47
	v_rcp_f32_e32 v50, v50
	v_rcp_f32_e32 v51, v51
	v_rcp_f32_e32 v48, v48
	v_rcp_f32_e32 v49, v49
	v_add_u32_e32 v52, 0x90, v148
	v_pk_mul_f32 v[34:35], v[38:39], v[34:35]
	v_pk_mul_f32 v[32:33], v[36:37], v[32:33]
	v_mad_i64_i32 v[52:53], s[42:43], v52, s57, v[140:141]
	v_pk_mul_f32 v[36:37], v[44:45], v[34:35]
	v_pk_mul_f32 v[34:35], v[46:47], v[32:33]
	v_pk_mul_f32 v[42:43], v[48:49], v[42:43]
	v_pk_mul_f32 v[40:41], v[50:51], v[40:41]
	v_lshl_add_u64 v[38:39], v[52:53], 0, v[112:113]
	v_cvt_pk_bf16_f32 v32, v40, v41
	v_cvt_pk_bf16_f32 v33, v42, v43
	v_cvt_pk_bf16_f32 v34, v34, v35
	v_cvt_pk_bf16_f32 v35, v36, v37
	global_store_dwordx4 v[38:39], v[32:35], off
	v_pk_mul_f32 v[26:27], v[30:31], v[26:27]
	v_pk_mul_f32 v[24:25], v[28:29], v[24:25]
	v_pk_mul_f32 v[32:33], v[30:31], s[22:23] op_sel_hi:[1,0]
	v_pk_mul_f32 v[34:35], v[28:29], s[22:23] op_sel_hi:[1,0]
	v_pk_mul_f32 v[28:29], v[22:23], s[22:23] op_sel_hi:[1,0]
	v_pk_mul_f32 v[30:31], v[20:21], s[22:23] op_sel_hi:[1,0]
	v_exp_f32_e32 v28, v28
	v_exp_f32_e32 v30, v30
	v_exp_f32_e32 v29, v29
	v_exp_f32_e32 v31, v31
	v_exp_f32_e32 v34, v34
	v_exp_f32_e32 v32, v32
	v_exp_f32_e32 v33, v33
	v_exp_f32_e32 v35, v35
	v_pk_add_f32 v[28:29], v[28:29], 1.0 op_sel_hi:[1,0]
	v_pk_add_f32 v[30:31], v[30:31], 1.0 op_sel_hi:[1,0]
	v_pk_add_f32 v[32:33], v[32:33], 1.0 op_sel_hi:[1,0]
	v_pk_add_f32 v[34:35], v[34:35], 1.0 op_sel_hi:[1,0]
	v_rcp_f32_e32 v30, v30
	v_rcp_f32_e32 v28, v28
	v_rcp_f32_e32 v29, v29
	v_rcp_f32_e32 v31, v31
	v_rcp_f32_e32 v34, v34
	v_rcp_f32_e32 v35, v35
	v_rcp_f32_e32 v32, v32
	v_rcp_f32_e32 v33, v33
	v_add_u32_e32 v36, 0xa0, v148
	v_pk_mul_f32 v[18:19], v[22:23], v[18:19]
	v_pk_mul_f32 v[16:17], v[20:21], v[16:17]
	v_mad_i64_i32 v[36:37], s[42:43], v36, s57, v[140:141]
	v_pk_mul_f32 v[20:21], v[28:29], v[18:19]
	v_pk_mul_f32 v[18:19], v[30:31], v[16:17]
	v_pk_mul_f32 v[26:27], v[32:33], v[26:27]
	v_pk_mul_f32 v[24:25], v[34:35], v[24:25]
	v_lshl_add_u64 v[22:23], v[36:37], 0, v[112:113]
	v_cvt_pk_bf16_f32 v16, v24, v25
	v_cvt_pk_bf16_f32 v17, v26, v27
	v_cvt_pk_bf16_f32 v18, v18, v19
	v_cvt_pk_bf16_f32 v19, v20, v21
	global_store_dwordx4 v[22:23], v[16:19], off
	v_pk_mul_f32 v[10:11], v[14:15], v[10:11]
	v_pk_mul_f32 v[8:9], v[12:13], v[8:9]
	v_pk_mul_f32 v[16:17], v[14:15], s[22:23] op_sel_hi:[1,0]
	v_pk_mul_f32 v[18:19], v[12:13], s[22:23] op_sel_hi:[1,0]
	v_pk_mul_f32 v[12:13], v[6:7], s[22:23] op_sel_hi:[1,0]
	v_pk_mul_f32 v[14:15], v[4:5], s[22:23] op_sel_hi:[1,0]
	v_exp_f32_e32 v12, v12
	v_exp_f32_e32 v14, v14
	v_exp_f32_e32 v13, v13
	v_exp_f32_e32 v15, v15
	v_exp_f32_e32 v18, v18
	v_exp_f32_e32 v16, v16
	v_exp_f32_e32 v17, v17
	v_exp_f32_e32 v19, v19
	v_pk_add_f32 v[12:13], v[12:13], 1.0 op_sel_hi:[1,0]
	v_pk_add_f32 v[14:15], v[14:15], 1.0 op_sel_hi:[1,0]
	v_pk_add_f32 v[16:17], v[16:17], 1.0 op_sel_hi:[1,0]
	v_pk_add_f32 v[18:19], v[18:19], 1.0 op_sel_hi:[1,0]
	v_rcp_f32_e32 v14, v14
	v_rcp_f32_e32 v12, v12
	v_rcp_f32_e32 v13, v13
	v_rcp_f32_e32 v15, v15
	v_rcp_f32_e32 v18, v18
	v_rcp_f32_e32 v19, v19
	v_rcp_f32_e32 v16, v16
	v_rcp_f32_e32 v17, v17
	v_add_u32_e32 v20, 0xb0, v148
	v_mad_i64_i32 v[20:21], s[42:43], v20, s57, v[140:141]
	v_pk_mul_f32 v[2:3], v[6:7], v[2:3]
	v_pk_mul_f32 v[0:1], v[4:5], v[0:1]
	v_pk_mul_f32 v[4:5], v[12:13], v[2:3]
	v_pk_mul_f32 v[2:3], v[14:15], v[0:1]
	v_lshl_add_u64 v[6:7], v[20:21], 0, v[112:113]
	s_andn2_b64 vcc, exec, s[6:7]
	s_mov_b64 s[6:7], -1
	v_pk_mul_f32 v[10:11], v[16:17], v[10:11]
	v_pk_mul_f32 v[8:9], v[18:19], v[8:9]
	v_cvt_pk_bf16_f32 v1, v10, v11
	v_cvt_pk_bf16_f32 v2, v2, v3
	v_cvt_pk_bf16_f32 v3, v4, v5
	s_nop 0
	v_cvt_pk_bf16_f32 v0, v8, v9
	global_store_dwordx4 v[6:7], v[0:3], off
	s_cbranch_vccnz .LBB0_1243
	s_andn2_b64 vcc, exec, s[0:1]
	s_cbranch_vccnz .LBB0_1242
	s_barrier
	s_branch .LBB0_1242

; __device__ __forceinline__ unsigned cvt_pk_bf16(float lo, float hi) { unsigned r; asm("v_cvt_pk_bf16_f32 %0, %1, %2" : "=v"(r) : "v"(lo), "v"(hi)); return r; }
;     __device__ __forceinline__ void operator()(const Acc& acc, const Unit& u, int wr, int wc, int fr, int fq) const {
;         const int row0 = u.pm * 256 + wr * 64 + fr, h0 = u.pn * 128 + wc * 32 + 8 * fq;
; #pragma unroll
;         for (int ai = 0; ai < 2; ++ai)
; #pragma unroll
;             for (int m = 0; m < 4; ++m) { bf16_t* rp = ACT + (size_t)(row0 + ai * 128 + m * 16) * FF + h0; float v[8];
; #pragma unroll
;                 for (int n = 0; n < 2; ++n) { const f32x4 a = acc[ai][0][m][n], b = acc[ai][1][m][n];
;                     const f32x4 t = a * (-LOG2E); f32x4 e; e.x = __builtin_amdgcn_exp2f(t.x); e.y = __builtin_amdgcn_exp2f(t.y); e.z = __builtin_amdgcn_exp2f(t.z); e.w = __builtin_amdgcn_exp2f(t.w);
;                     const f32x4 d = e + 1.0f; f32x4 r; r.x = __builtin_amdgcn_rcpf(d.x); r.y = __builtin_amdgcn_rcpf(d.y); r.z = __builtin_amdgcn_rcpf(d.z); r.w = __builtin_amdgcn_rcpf(d.w);
;                     const f32x4 o = (a * b) * r; v[4 * n + 0] = o.x; v[4 * n + 1] = o.y; v[4 * n + 2] = o.z; v[4 * n + 3] = o.w; }
;                 u32x4 w; w.x = cvt_pk_bf16(v[0], v[1]); w.y = cvt_pk_bf16(v[2], v[3]); w.z = cvt_pk_bf16(v[4], v[5]); w.w = cvt_pk_bf16(v[6], v[7]); __builtin_nontemporal_store(w, (u32x4*)rp); }
.LBB0_1866:
	v_pk_mul_f32 v[152:153], v[126:127], s[12:13] op_sel_hi:[1,0]
	v_pk_mul_f32 v[122:123], v[126:127], v[122:123]
	v_pk_mul_f32 v[126:127], v[116:117], s[12:13] op_sel_hi:[1,0]
	v_pk_mul_f32 v[154:155], v[124:125], s[12:13] op_sel_hi:[1,0]
	v_pk_mul_f32 v[120:121], v[124:125], v[120:121]
	v_pk_mul_f32 v[124:125], v[118:119], s[12:13] op_sel_hi:[1,0]
	v_exp_f32_e32 v126, v126
	v_exp_f32_e32 v127, v127
	v_exp_f32_e32 v154, v154
	v_exp_f32_e32 v152, v152
	v_exp_f32_e32 v153, v153
	v_exp_f32_e32 v155, v155
	v_exp_f32_e32 v124, v124
	v_exp_f32_e32 v125, v125
	v_pk_add_f32 v[126:127], v[126:127], 1.0 op_sel_hi:[1,0]
	v_pk_add_f32 v[152:153], v[152:153], 1.0 op_sel_hi:[1,0]
	v_pk_add_f32 v[154:155], v[154:155], 1.0 op_sel_hi:[1,0]
	v_pk_add_f32 v[124:125], v[124:125], 1.0 op_sel_hi:[1,0]
	v_rcp_f32_e32 v126, v126
	v_rcp_f32_e32 v127, v127
	v_rcp_f32_e32 v154, v154
	v_rcp_f32_e32 v155, v155
	v_rcp_f32_e32 v152, v152
	v_rcp_f32_e32 v153, v153
	v_rcp_f32_e32 v124, v124
	v_rcp_f32_e32 v125, v125
	v_lshl_or_b32 v150, s53, 7, v144
	v_lshl_add_u32 v148, s34, 8, v142
	v_ashrrev_i32_e32 v151, 31, v150
	v_mov_b64_e32 v[140:141], s[14:15]
	v_pk_mul_f32 v[112:113], v[116:117], v[112:113]
	v_mad_i64_i32 v[156:157], s[36:37], v148, s52, v[140:141]
	v_pk_mul_f32 v[114:115], v[118:119], v[114:115]
	v_pk_mul_f32 v[116:117], v[126:127], v[112:113]
	v_lshlrev_b64 v[112:113], 1, v[150:151]
	v_pk_mul_f32 v[122:123], v[152:153], v[122:123]
	v_pk_mul_f32 v[120:121], v[154:155], v[120:121]
	v_pk_mul_f32 v[118:119], v[124:125], v[114:115]
	v_lshl_add_u64 v[124:125], v[156:157], 0, v[112:113]
	v_cvt_pk_bf16_f32 v114, v120, v121
	v_cvt_pk_bf16_f32 v115, v122, v123
	v_cvt_pk_bf16_f32 v116, v116, v117
	v_cvt_pk_bf16_f32 v117, v118, v119
	global_store_dwordx4 v[124:125], v[114:117], off
	v_pk_mul_f32 v[106:107], v[110:111], v[106:107]
	v_pk_mul_f32 v[104:105], v[108:109], v[104:105]
	v_pk_mul_f32 v[114:115], v[110:111], s[12:13] op_sel_hi:[1,0]
	v_pk_mul_f32 v[116:117], v[108:109], s[12:13] op_sel_hi:[1,0]
	v_pk_mul_f32 v[108:109], v[102:103], s[12:13] op_sel_hi:[1,0]
	v_pk_mul_f32 v[110:111], v[100:101], s[12:13] op_sel_hi:[1,0]
	v_exp_f32_e32 v108, v108
	v_exp_f32_e32 v110, v110
	v_exp_f32_e32 v109, v109
	v_exp_f32_e32 v111, v111
	v_exp_f32_e32 v116, v116
	v_exp_f32_e32 v114, v114
	v_exp_f32_e32 v115, v115
	v_exp_f32_e32 v117, v117
	v_pk_add_f32 v[108:109], v[108:109], 1.0 op_sel_hi:[1,0]
	v_pk_add_f32 v[110:111], v[110:111], 1.0 op_sel_hi:[1,0]
	v_pk_add_f32 v[114:115], v[114:115], 1.0 op_sel_hi:[1,0]
	v_pk_add_f32 v[116:117], v[116:117], 1.0 op_sel_hi:[1,0]
	v_rcp_f32_e32 v110, v110
	v_rcp_f32_e32 v108, v108
	v_rcp_f32_e32 v109, v109
	v_rcp_f32_e32 v111, v111
	v_rcp_f32_e32 v116, v116
	v_rcp_f32_e32 v117, v117
	v_rcp_f32_e32 v114, v114
	v_rcp_f32_e32 v115, v115
	v_or_b32_e32 v118, 16, v148
	v_pk_mul_f32 v[98:99], v[102:103], v[98:99]
	v_pk_mul_f32 v[96:97], v[100:101], v[96:97]
	v_mad_i64_i32 v[118:119], s[36:37], v118, s52, v[140:141]
	v_pk_mul_f32 v[100:101], v[108:109], v[98:99]
	v_pk_mul_f32 v[98:99], v[110:111], v[96:97]
	v_pk_mul_f32 v[106:107], v[114:115], v[106:107]
	v_pk_mul_f32 v[104:105], v[116:117], v[104:105]
	v_lshl_add_u64 v[102:103], v[118:119], 0, v[112:113]
	v_cvt_pk_bf16_f32 v96, v104, v105
	v_cvt_pk_bf16_f32 v97, v106, v107
	v_cvt_pk_bf16_f32 v98, v98, v99
	v_cvt_pk_bf16_f32 v99, v100, v101
	global_store_dwordx4 v[102:103], v[96:99], off
	v_pk_mul_f32 v[90:91], v[94:95], v[90:91]
	v_pk_mul_f32 v[88:89], v[92:93], v[88:89]
	v_pk_mul_f32 v[96:97], v[94:95], s[12:13] op_sel_hi:[1,0]
	v_pk_mul_f32 v[98:99], v[92:93], s[12:13] op_sel_hi:[1,0]
	v_pk_mul_f32 v[92:93], v[86:87], s[12:13] op_sel_hi:[1,0]
	v_pk_mul_f32 v[94:95], v[84:85], s[12:13] op_sel_hi:[1,0]
	v_exp_f32_e32 v92, v92
	v_exp_f32_e32 v94, v94
	v_exp_f32_e32 v93, v93
	v_exp_f32_e32 v95, v95
	v_exp_f32_e32 v98, v98
	v_exp_f32_e32 v96, v96
	v_exp_f32_e32 v97, v97
	v_exp_f32_e32 v99, v99
	v_pk_add_f32 v[92:93], v[92:93], 1.0 op_sel_hi:[1,0]
	v_pk_add_f32 v[94:95], v[94:95], 1.0 op_sel_hi:[1,0]
	v_pk_add_f32 v[96:97], v[96:97], 1.0 op_sel_hi:[1,0]
	v_pk_add_f32 v[98:99], v[98:99], 1.0 op_sel_hi:[1,0]
	v_rcp_f32_e32 v94, v94
	v_rcp_f32_e32 v92, v92
	v_rcp_f32_e32 v93, v93
	v_rcp_f32_e32 v95, v95
	v_rcp_f32_e32 v98, v98
	v_rcp_f32_e32 v99, v99
	v_rcp_f32_e32 v96, v96
	v_rcp_f32_e32 v97, v97
	v_or_b32_e32 v100, 32, v148
	v_pk_mul_f32 v[82:83], v[86:87], v[82:83]
	v_pk_mul_f32 v[80:81], v[84:85], v[80:81]
	v_mad_i64_i32 v[100:101], s[36:37], v100, s52, v[140:141]
	v_pk_mul_f32 v[84:85], v[92:93], v[82:83]
	v_pk_mul_f32 v[82:83], v[94:95], v[80:81]
	v_pk_mul_f32 v[90:91], v[96:97], v[90:91]
	v_pk_mul_f32 v[88:89], v[98:99], v[88:89]
	v_lshl_add_u64 v[86:87], v[100:101], 0, v[112:113]
	v_cvt_pk_bf16_f32 v80, v88, v89
	v_cvt_pk_bf16_f32 v81, v90, v91
	v_cvt_pk_bf16_f32 v82, v82, v83
	v_cvt_pk_bf16_f32 v83, v84, v85
	global_store_dwordx4 v[86:87], v[80:83], off
	v_pk_mul_f32 v[74:75], v[78:79], v[74:75]
	v_pk_mul_f32 v[72:73], v[76:77], v[72:73]
	v_pk_mul_f32 v[80:81], v[78:79], s[12:13] op_sel_hi:[1,0]
	v_pk_mul_f32 v[82:83], v[76:77], s[12:13] op_sel_hi:[1,0]
	v_pk_mul_f32 v[76:77], v[70:71], s[12:13] op_sel_hi:[1,0]
	v_pk_mul_f32 v[78:79], v[68:69], s[12:13] op_sel_hi:[1,0]
	v_exp_f32_e32 v76, v76
	v_exp_f32_e32 v78, v78
	v_exp_f32_e32 v77, v77
	v_exp_f32_e32 v79, v79
	v_exp_f32_e32 v82, v82
	v_exp_f32_e32 v80, v80
	v_exp_f32_e32 v81, v81
	v_exp_f32_e32 v83, v83
	v_pk_add_f32 v[76:77], v[76:77], 1.0 op_sel_hi:[1,0]
	v_pk_add_f32 v[78:79], v[78:79], 1.0 op_sel_hi:[1,0]
	v_pk_add_f32 v[80:81], v[80:81], 1.0 op_sel_hi:[1,0]
	v_pk_add_f32 v[82:83], v[82:83], 1.0 op_sel_hi:[1,0]
	v_rcp_f32_e32 v78, v78
; __device__ __forceinline__ unsigned cvt_pk_bf16(float lo, float hi) { unsigned r; asm("v_cvt_pk_bf16_f32 %0, %1, %2" : "=v"(r) : "v"(lo), "v"(hi)); return r; }
;     __device__ __forceinline__ void operator()(const Acc& acc, const Unit& u, int wr, int wc, int fr, int fq) const {
;         const int row0 = u.pm * 256 + wr * 64 + fr, h0 = u.pn * 128 + wc * 32 + 8 * fq;
; #pragma unroll
;         for (int ai = 0; ai < 2; ++ai)
; #pragma unroll
;             for (int m = 0; m < 4; ++m) { bf16_t* rp = ACT + (size_t)(row0 + ai * 128 + m * 16) * FF + h0; float v[8];
; #pragma unroll
;                 for (int n = 0; n < 2; ++n) { const f32x4 a = acc[ai][0][m][n], b = acc[ai][1][m][n];
;                     const f32x4 t = a * (-LOG2E); f32x4 e; e.x = __builtin_amdgcn_exp2f(t.x); e.y = __builtin_amdgcn_exp2f(t.y); e.z = __builtin_amdgcn_exp2f(t.z); e.w = __builtin_amdgcn_exp2f(t.w);
;                     const f32x4 d = e + 1.0f; f32x4 r; r.x = __builtin_amdgcn_rcpf(d.x); r.y = __builtin_amdgcn_rcpf(d.y); r.z = __builtin_amdgcn_rcpf(d.z); r.w = __builtin_amdgcn_rcpf(d.w);
;                     const f32x4 o = (a * b) * r; v[4 * n + 0] = o.x; v[4 * n + 1] = o.y; v[4 * n + 2] = o.z; v[4 * n + 3] = o.w; }
;                 u32x4 w; w.x = cvt_pk_bf16(v[0], v[1]); w.y = cvt_pk_bf16(v[2], v[3]); w.z = cvt_pk_bf16(v[4], v[5]); w.w = cvt_pk_bf16(v[6], v[7]); __builtin_nontemporal_store(w, (u32x4*)rp); }
	v_rcp_f32_e32 v76, v76
	v_rcp_f32_e32 v77, v77
	v_rcp_f32_e32 v79, v79
	v_rcp_f32_e32 v82, v82
	v_rcp_f32_e32 v83, v83
	v_rcp_f32_e32 v80, v80
	v_rcp_f32_e32 v81, v81
	v_or_b32_e32 v84, 48, v148
	v_pk_mul_f32 v[66:67], v[70:71], v[66:67]
	v_pk_mul_f32 v[64:65], v[68:69], v[64:65]
	v_mad_i64_i32 v[84:85], s[36:37], v84, s52, v[140:141]
	v_pk_mul_f32 v[68:69], v[76:77], v[66:67]
	v_pk_mul_f32 v[66:67], v[78:79], v[64:65]
	v_pk_mul_f32 v[74:75], v[80:81], v[74:75]
	v_pk_mul_f32 v[72:73], v[82:83], v[72:73]
	v_lshl_add_u64 v[70:71], v[84:85], 0, v[112:113]
	v_cvt_pk_bf16_f32 v64, v72, v73
	v_cvt_pk_bf16_f32 v65, v74, v75
	v_cvt_pk_bf16_f32 v66, v66, v67
	v_cvt_pk_bf16_f32 v67, v68, v69
	global_store_dwordx4 v[70:71], v[64:67], off
	v_pk_mul_f32 v[58:59], v[62:63], v[58:59]
	v_pk_mul_f32 v[56:57], v[60:61], v[56:57]
	v_pk_mul_f32 v[64:65], v[62:63], s[12:13] op_sel_hi:[1,0]
	v_pk_mul_f32 v[66:67], v[60:61], s[12:13] op_sel_hi:[1,0]
	v_pk_mul_f32 v[60:61], v[54:55], s[12:13] op_sel_hi:[1,0]
	v_pk_mul_f32 v[62:63], v[52:53], s[12:13] op_sel_hi:[1,0]
	v_exp_f32_e32 v60, v60
	v_exp_f32_e32 v62, v62
	v_exp_f32_e32 v61, v61
	v_exp_f32_e32 v63, v63
	v_exp_f32_e32 v66, v66
	v_exp_f32_e32 v64, v64
	v_exp_f32_e32 v65, v65
	v_exp_f32_e32 v67, v67
	v_pk_add_f32 v[60:61], v[60:61], 1.0 op_sel_hi:[1,0]
	v_pk_add_f32 v[62:63], v[62:63], 1.0 op_sel_hi:[1,0]
	v_pk_add_f32 v[64:65], v[64:65], 1.0 op_sel_hi:[1,0]
	v_pk_add_f32 v[66:67], v[66:67], 1.0 op_sel_hi:[1,0]
	v_rcp_f32_e32 v62, v62
	v_rcp_f32_e32 v60, v60
	v_rcp_f32_e32 v61, v61
	v_rcp_f32_e32 v63, v63
	v_rcp_f32_e32 v66, v66
	v_rcp_f32_e32 v67, v67
	v_rcp_f32_e32 v64, v64
	v_rcp_f32_e32 v65, v65
	v_add_u32_e32 v68, 0x80, v148
	v_pk_mul_f32 v[50:51], v[54:55], v[50:51]
	v_pk_mul_f32 v[48:49], v[52:53], v[48:49]
	v_mad_i64_i32 v[68:69], s[36:37], v68, s52, v[140:141]
	v_pk_mul_f32 v[52:53], v[60:61], v[50:51]
	v_pk_mul_f32 v[50:51], v[62:63], v[48:49]
	v_pk_mul_f32 v[58:59], v[64:65], v[58:59]
	v_pk_mul_f32 v[56:57], v[66:67], v[56:57]
	v_lshl_add_u64 v[54:55], v[68:69], 0, v[112:113]
	v_cvt_pk_bf16_f32 v48, v56, v57
	v_cvt_pk_bf16_f32 v49, v58, v59
	v_cvt_pk_bf16_f32 v50, v50, v51
	v_cvt_pk_bf16_f32 v51, v52, v53
	global_store_dwordx4 v[54:55], v[48:51], off
	v_pk_mul_f32 v[42:43], v[46:47], v[42:43]
	v_pk_mul_f32 v[40:41], v[44:45], v[40:41]
	v_pk_mul_f32 v[48:49], v[46:47], s[12:13] op_sel_hi:[1,0]
	v_pk_mul_f32 v[50:51], v[44:45], s[12:13] op_sel_hi:[1,0]
	v_pk_mul_f32 v[44:45], v[38:39], s[12:13] op_sel_hi:[1,0]
	v_pk_mul_f32 v[46:47], v[36:37], s[12:13] op_sel_hi:[1,0]
	v_exp_f32_e32 v44, v44
	v_exp_f32_e32 v46, v46
	v_exp_f32_e32 v45, v45
	v_exp_f32_e32 v47, v47
	v_exp_f32_e32 v50, v50
	v_exp_f32_e32 v48, v48
	v_exp_f32_e32 v49, v49
	v_exp_f32_e32 v51, v51
	v_pk_add_f32 v[44:45], v[44:45], 1.0 op_sel_hi:[1,0]
	v_pk_add_f32 v[46:47], v[46:47], 1.0 op_sel_hi:[1,0]
	v_pk_add_f32 v[48:49], v[48:49], 1.0 op_sel_hi:[1,0]
	v_pk_add_f32 v[50:51], v[50:51], 1.0 op_sel_hi:[1,0]
	v_rcp_f32_e32 v46, v46
	v_rcp_f32_e32 v44, v44
	v_rcp_f32_e32 v45, v45
	v_rcp_f32_e32 v47, v47
	v_rcp_f32_e32 v50, v50
	v_rcp_f32_e32 v51, v51
	v_rcp_f32_e32 v48, v48
	v_rcp_f32_e32 v49, v49
	v_add_u32_e32 v52, 0x90, v148
	v_pk_mul_f32 v[34:35], v[38:39], v[34:35]
	v_pk_mul_f32 v[32:33], v[36:37], v[32:33]
	v_mad_i64_i32 v[52:53], s[36:37], v52, s52, v[140:141]
	v_pk_mul_f32 v[36:37], v[44:45], v[34:35]
	v_pk_mul_f32 v[34:35], v[46:47], v[32:33]
	v_pk_mul_f32 v[42:43], v[48:49], v[42:43]
	v_pk_mul_f32 v[40:41], v[50:51], v[40:41]
	v_lshl_add_u64 v[38:39], v[52:53], 0, v[112:113]
	v_cvt_pk_bf16_f32 v32, v40, v41
	v_cvt_pk_bf16_f32 v33, v42, v43
	v_cvt_pk_bf16_f32 v34, v34, v35
	v_cvt_pk_bf16_f32 v35, v36, v37
	global_store_dwordx4 v[38:39], v[32:35], off
	v_pk_mul_f32 v[26:27], v[30:31], v[26:27]
	v_pk_mul_f32 v[24:25], v[28:29], v[24:25]
	v_pk_mul_f32 v[32:33], v[30:31], s[12:13] op_sel_hi:[1,0]
	v_pk_mul_f32 v[34:35], v[28:29], s[12:13] op_sel_hi:[1,0]
	v_pk_mul_f32 v[28:29], v[22:23], s[12:13] op_sel_hi:[1,0]
	v_pk_mul_f32 v[30:31], v[20:21], s[12:13] op_sel_hi:[1,0]
	v_exp_f32_e32 v28, v28
	v_exp_f32_e32 v30, v30
	v_exp_f32_e32 v29, v29
	v_exp_f32_e32 v31, v31
	v_exp_f32_e32 v34, v34
	v_exp_f32_e32 v32, v32
	v_exp_f32_e32 v33, v33
	v_exp_f32_e32 v35, v35
	v_pk_add_f32 v[28:29], v[28:29], 1.0 op_sel_hi:[1,0]
	v_pk_add_f32 v[30:31], v[30:31], 1.0 op_sel_hi:[1,0]
	v_pk_add_f32 v[32:33], v[32:33], 1.0 op_sel_hi:[1,0]
	v_pk_add_f32 v[34:35], v[34:35], 1.0 op_sel_hi:[1,0]
	v_rcp_f32_e32 v30, v30
	v_rcp_f32_e32 v28, v28
	v_rcp_f32_e32 v29, v29
	v_rcp_f32_e32 v31, v31
	v_rcp_f32_e32 v34, v34
	v_rcp_f32_e32 v35, v35
	v_rcp_f32_e32 v32, v32
	v_rcp_f32_e32 v33, v33
	v_add_u32_e32 v36, 0xa0, v148
	v_pk_mul_f32 v[18:19], v[22:23], v[18:19]
	v_pk_mul_f32 v[16:17], v[20:21], v[16:17]
	v_mad_i64_i32 v[36:37], s[36:37], v36, s52, v[140:141]
	v_pk_mul_f32 v[20:21], v[28:29], v[18:19]
	v_pk_mul_f32 v[18:19], v[30:31], v[16:17]
	v_pk_mul_f32 v[26:27], v[32:33], v[26:27]
	v_pk_mul_f32 v[24:25], v[34:35], v[24:25]
	v_lshl_add_u64 v[22:23], v[36:37], 0, v[112:113]
	v_cvt_pk_bf16_f32 v16, v24, v25
	v_cvt_pk_bf16_f32 v17, v26, v27
	v_cvt_pk_bf16_f32 v18, v18, v19
	v_cvt_pk_bf16_f32 v19, v20, v21
	global_store_dwordx4 v[22:23], v[16:19], off
	v_pk_mul_f32 v[10:11], v[14:15], v[10:11]
	v_pk_mul_f32 v[8:9], v[12:13], v[8:9]
	v_pk_mul_f32 v[16:17], v[14:15], s[12:13] op_sel_hi:[1,0]
	v_pk_mul_f32 v[18:19], v[12:13], s[12:13] op_sel_hi:[1,0]
	v_pk_mul_f32 v[12:13], v[6:7], s[12:13] op_sel_hi:[1,0]
	v_pk_mul_f32 v[14:15], v[4:5], s[12:13] op_sel_hi:[1,0]
	v_exp_f32_e32 v12, v12
	v_exp_f32_e32 v14, v14
	v_exp_f32_e32 v13, v13
	v_exp_f32_e32 v15, v15
	v_exp_f32_e32 v18, v18
	v_exp_f32_e32 v16, v16
	v_exp_f32_e32 v17, v17
	v_exp_f32_e32 v19, v19
	v_pk_add_f32 v[12:13], v[12:13], 1.0 op_sel_hi:[1,0]
	v_pk_add_f32 v[14:15], v[14:15], 1.0 op_sel_hi:[1,0]
	v_pk_add_f32 v[16:17], v[16:17], 1.0 op_sel_hi:[1,0]
	v_pk_add_f32 v[18:19], v[18:19], 1.0 op_sel_hi:[1,0]
	v_rcp_f32_e32 v14, v14
	v_rcp_f32_e32 v12, v12
	v_rcp_f32_e32 v13, v13
	v_rcp_f32_e32 v15, v15
	v_rcp_f32_e32 v18, v18
	v_rcp_f32_e32 v19, v19
	v_rcp_f32_e32 v16, v16
	v_rcp_f32_e32 v17, v17
	v_add_u32_e32 v20, 0xb0, v148
	v_mad_i64_i32 v[20:21], s[36:37], v20, s52, v[140:141]
	v_pk_mul_f32 v[2:3], v[6:7], v[2:3]
	v_pk_mul_f32 v[0:1], v[4:5], v[0:1]
	v_pk_mul_f32 v[4:5], v[12:13], v[2:3]
	v_pk_mul_f32 v[2:3], v[14:15], v[0:1]
	v_lshl_add_u64 v[6:7], v[20:21], 0, v[112:113]
	s_andn2_b64 vcc, exec, s[6:7]
	s_mov_b64 s[6:7], -1
	v_pk_mul_f32 v[10:11], v[16:17], v[10:11]
	v_pk_mul_f32 v[8:9], v[18:19], v[8:9]
	v_cvt_pk_bf16_f32 v1, v10, v11
	v_cvt_pk_bf16_f32 v2, v2, v3
	v_cvt_pk_bf16_f32 v3, v4, v5
	s_nop 0
	v_cvt_pk_bf16_f32 v0, v8, v9
	global_store_dwordx4 v[6:7], v[0:3], off
	s_cbranch_vccnz .LBB0_1859
	s_andn2_b64 vcc, exec, s[0:1]
	s_cbranch_vccnz .LBB0_1858
	s_barrier
	s_branch .LBB0_1858
